# v11 + nt hint on prologue f32 weight loads and on attention Q/K/V loads (streamed once)
# baseline (speedup 1.0000x reference)
; #define LAS __attribute__((address_space(3)))
; __device__ __forceinline__ void p0_transpose_item(const float* W, const float* gain, int K, int N, bf16* WT, LAS float* scr, int item, int lane) {
;     const int nblk = N / 32, kb = item / nblk, nb = item % nblk, k0 = 64 * kb, n0 = 32 * nb;
;     float tv[32];
; #pragma unroll
;     for (int i = 0; i < 32; ++i) { const int kk = 2 * i + (lane >> 5); tv[i] = W[(size_t)(k0 + kk) * N + n0 + (lane & 31)]; }
; __device__ __forceinline__ void p0_prologue(const Frame& F, const Ptrs& A) {
;     ...
;     for (int it = gw; it < 2 * I_LAYER; it += NGW) {
;         const int l = it / I_LAYER; int r = it - l * I_LAYER;
;         unsigned char* wl = A.ws + WS_W + (size_t)l * W_LAYER;
;         if (r < I_IN) { p0_transpose_item(A.w_in + (size_t)l * DM * DIN, A.mix_norm + l * DM, DM, DIN, (bf16*)(wl + W_IN), scr, r, F.lane); continue; } r -= I_IN;
;         if (r < I_A) { p0_transpose_item(A.w_a + (size_t)l * 512 * DM, nullptr, 512, DM, (bf16*)(wl + W_A), scr, r, F.lane); continue; } r -= I_A;
;         if (r < I_B) { p0_transpose_item(A.w_b + (size_t)l * DM * DM, nullptr, DM, DM, (bf16*)(wl + W_B), scr, r, F.lane); continue; } r -= I_B;
;         if (r < I_O) { p0_transpose_item(A.w_o + (size_t)l * DM * DM, nullptr, DM, DM, (bf16*)(wl + W_O), scr, r, F.lane); continue; } r -= I_O;
;         if (r < I_UP) { p0_transpose_item(A.w_up + (size_t)l * DM * DFF, A.ffn_norm + l * DM, DM, DFF, (bf16*)(wl + W_UP), scr, r, F.lane); continue; } r -= I_UP;
;         p0_transpose_item(A.w_down + (size_t)l * DFF * DM, nullptr, DFF, DM, (bf16*)(wl + W_DN), scr, r, F.lane);
.LBB0_10:
	s_mul_hi_i32 s6, s92, 0x66666667
	s_lshr_b32 s30, s6, 31
	s_ashr_i32 s6, s6, 12
	s_add_i32 s30, s6, s30
	s_mul_i32 s6, s30, 0xffffd800
	s_add_i32 s38, s92, s6
	s_ashr_i32 s31, s30, 31
	s_mul_i32 s34, s30, 0x2800000
	s_mul_hi_i32 s6, s30, 0x2800000
	s_add_u32 s93, s42, s34
	s_addc_u32 s94, s43, s6
	s_cmpk_gt_i32 s38, 0x12ff
	s_mov_b64 s[34:35], -1
	s_cbranch_scc0 .LBB0_30
	s_cmpk_gt_u32 s38, 0x13ff
	s_cbranch_scc0 .LBB0_27
	s_cmpk_gt_u32 s38, 0x15ff
	s_cbranch_scc0 .LBB0_24
	s_cmpk_gt_u32 s38, 0x17ff
	s_cbranch_scc0 .LBB0_21
	s_cmpk_gt_u32 s38, 0x1fff
	s_cbranch_scc0 .LBB0_16
	s_lshl_b64 s[34:35], s[30:31], 24
	s_add_u32 s39, s56, s34
	s_mul_i32 s6, s30, 0xffffb000
	s_addc_u32 s35, s57, s35
	s_add_i32 s6, s46, s6
	s_andn2_b32 s6, s6, 63
	s_addk_i32 s6, 0xc000
	s_and_b32 s34, s44, 0x3e0
	v_or_b32_e32 v6, s6, v1
	s_lshl_b32 s95, s34, 2
	s_add_u32 s96, s39, s95
	v_or_b32_e32 v12, 2, v6
	v_or_b32_e32 v14, 4, v6
	v_or_b32_e32 v16, 6, v6
	v_or_b32_e32 v18, 8, v6
	v_or_b32_e32 v20, 10, v6
	v_or_b32_e32 v22, 12, v6
	v_or_b32_e32 v24, 14, v6
	s_addc_u32 s97, s35, 0
	v_ashrrev_i32_e32 v7, 31, v6
	v_ashrrev_i32_e32 v13, 31, v12
	v_ashrrev_i32_e32 v15, 31, v14
	v_ashrrev_i32_e32 v17, 31, v16
	v_ashrrev_i32_e32 v19, 31, v18
	v_ashrrev_i32_e32 v21, 31, v20
	v_ashrrev_i32_e32 v23, 31, v22
	v_ashrrev_i32_e32 v25, 31, v24
	v_lshl_add_u64 v[8:9], s[96:97], 0, v[2:3]
	v_lshlrev_b64 v[10:11], 12, v[6:7]
	v_lshlrev_b64 v[12:13], 12, v[12:13]
	v_lshlrev_b64 v[14:15], 12, v[14:15]
	v_lshlrev_b64 v[16:17], 12, v[16:17]
	v_lshlrev_b64 v[18:19], 12, v[18:19]
	v_lshlrev_b64 v[20:21], 12, v[20:21]
	v_lshlrev_b64 v[22:23], 12, v[22:23]
	v_lshlrev_b64 v[24:25], 12, v[24:25]
	v_lshl_add_u64 v[10:11], v[8:9], 0, v[10:11]
	v_lshl_add_u64 v[12:13], v[8:9], 0, v[12:13]
	v_lshl_add_u64 v[14:15], v[8:9], 0, v[14:15]
	v_lshl_add_u64 v[16:17], v[8:9], 0, v[16:17]
	v_lshl_add_u64 v[18:19], v[8:9], 0, v[18:19]
	v_lshl_add_u64 v[20:21], v[8:9], 0, v[20:21]
	v_lshl_add_u64 v[22:23], v[8:9], 0, v[22:23]
	v_lshl_add_u64 v[24:25], v[8:9], 0, v[24:25]
	global_load_dword v5, v[10:11], off nt
	global_load_dword v26, v[12:13], off nt
	global_load_dword v27, v[14:15], off nt
	global_load_dword v28, v[16:17], off nt
	global_load_dword v29, v[18:19], off nt
	global_load_dword v30, v[20:21], off nt
	global_load_dword v31, v[22:23], off nt
	global_load_dword v32, v[24:25], off nt
	v_or_b32_e32 v10, 16, v6
	v_or_b32_e32 v12, 18, v6
	v_or_b32_e32 v14, 20, v6
	v_or_b32_e32 v16, 22, v6
	v_or_b32_e32 v18, 24, v6
	v_or_b32_e32 v20, 26, v6
	v_or_b32_e32 v22, 28, v6
	v_or_b32_e32 v24, 30, v6
	v_ashrrev_i32_e32 v11, 31, v10
	v_ashrrev_i32_e32 v13, 31, v12
	v_ashrrev_i32_e32 v15, 31, v14
	v_ashrrev_i32_e32 v17, 31, v16
	v_ashrrev_i32_e32 v19, 31, v18
	v_ashrrev_i32_e32 v21, 31, v20
	v_ashrrev_i32_e32 v23, 31, v22
	v_ashrrev_i32_e32 v25, 31, v24
	v_lshlrev_b64 v[10:11], 12, v[10:11]
	v_lshlrev_b64 v[12:13], 12, v[12:13]
	v_lshlrev_b64 v[14:15], 12, v[14:15]
	v_lshlrev_b64 v[16:17], 12, v[16:17]
	v_lshlrev_b64 v[18:19], 12, v[18:19]
	v_lshlrev_b64 v[20:21], 12, v[20:21]
	v_lshlrev_b64 v[22:23], 12, v[22:23]
	v_lshlrev_b64 v[24:25], 12, v[24:25]
	v_lshl_add_u64 v[10:11], v[8:9], 0, v[10:11]
	v_lshl_add_u64 v[12:13], v[8:9], 0, v[12:13]
	v_lshl_add_u64 v[14:15], v[8:9], 0, v[14:15]
	v_lshl_add_u64 v[16:17], v[8:9], 0, v[16:17]
	v_lshl_add_u64 v[18:19], v[8:9], 0, v[18:19]
	v_lshl_add_u64 v[20:21], v[8:9], 0, v[20:21]
	v_lshl_add_u64 v[22:23], v[8:9], 0, v[22:23]
	v_lshl_add_u64 v[24:25], v[8:9], 0, v[24:25]
	global_load_dword v33, v[10:11], off nt
	global_load_dword v34, v[12:13], off nt
	global_load_dword v35, v[14:15], off nt
	global_load_dword v36, v[16:17], off nt
	global_load_dword v37, v[18:19], off nt
	global_load_dword v38, v[20:21], off nt
	global_load_dword v39, v[22:23], off nt
	global_load_dword v53, v[24:25], off nt
	v_or_b32_e32 v10, 32, v6
	v_or_b32_e32 v12, 34, v6
	v_or_b32_e32 v14, 36, v6
	v_or_b32_e32 v16, 38, v6
	v_or_b32_e32 v18, 40, v6
	v_or_b32_e32 v20, 42, v6
	v_or_b32_e32 v22, 44, v6
	v_or_b32_e32 v24, 46, v6
	v_ashrrev_i32_e32 v11, 31, v10
	v_ashrrev_i32_e32 v13, 31, v12
	v_ashrrev_i32_e32 v15, 31, v14
	v_ashrrev_i32_e32 v17, 31, v16
	v_ashrrev_i32_e32 v19, 31, v18
	v_ashrrev_i32_e32 v21, 31, v20
	v_ashrrev_i32_e32 v23, 31, v22
	v_ashrrev_i32_e32 v25, 31, v24
	v_lshlrev_b64 v[10:11], 12, v[10:11]
	v_lshlrev_b64 v[12:13], 12, v[12:13]
	v_lshlrev_b64 v[14:15], 12, v[14:15]
	v_lshlrev_b64 v[16:17], 12, v[16:17]
	v_lshlrev_b64 v[18:19], 12, v[18:19]
	v_lshlrev_b64 v[20:21], 12, v[20:21]
	v_lshlrev_b64 v[22:23], 12, v[22:23]
	v_lshlrev_b64 v[24:25], 12, v[24:25]
	v_lshl_add_u64 v[10:11], v[8:9], 0, v[10:11]
	v_lshl_add_u64 v[12:13], v[8:9], 0, v[12:13]
	v_lshl_add_u64 v[14:15], v[8:9], 0, v[14:15]
	v_lshl_add_u64 v[16:17], v[8:9], 0, v[16:17]
	v_lshl_add_u64 v[18:19], v[8:9], 0, v[18:19]
	v_lshl_add_u64 v[20:21], v[8:9], 0, v[20:21]
	v_lshl_add_u64 v[22:23], v[8:9], 0, v[22:23]
	v_lshl_add_u64 v[24:25], v[8:9], 0, v[24:25]
	global_load_dword v54, v[10:11], off nt
	global_load_dword v55, v[12:13], off nt
	global_load_dword v56, v[14:15], off nt
	global_load_dword v57, v[16:17], off nt
	global_load_dword v58, v[18:19], off nt
	global_load_dword v59, v[20:21], off nt
	global_load_dword v60, v[22:23], off nt
	s_nop 0
	global_load_dword v24, v[24:25], off nt
	v_or_b32_e32 v10, 48, v6
	v_or_b32_e32 v12, 50, v6
	v_or_b32_e32 v14, 52, v6
	v_or_b32_e32 v16, 54, v6
	v_or_b32_e32 v18, 56, v6
	v_or_b32_e32 v20, 58, v6
	v_or_b32_e32 v22, 60, v6
	v_or_b32_e32 v6, 62, v6
	v_ashrrev_i32_e32 v11, 31, v10
	v_ashrrev_i32_e32 v13, 31, v12
	v_ashrrev_i32_e32 v15, 31, v14
	v_ashrrev_i32_e32 v7, 31, v6
	v_lshlrev_b64 v[10:11], 12, v[10:11]
	v_lshlrev_b64 v[12:13], 12, v[12:13]
	v_lshlrev_b64 v[14:15], 12, v[14:15]
	v_ashrrev_i32_e32 v17, 31, v16
	v_ashrrev_i32_e32 v19, 31, v18
	v_ashrrev_i32_e32 v21, 31, v20
	v_ashrrev_i32_e32 v23, 31, v22
	v_lshlrev_b64 v[6:7], 12, v[6:7]
	v_lshl_add_u64 v[10:11], v[8:9], 0, v[10:11]
	v_lshl_add_u64 v[12:13], v[8:9], 0, v[12:13]
	v_lshl_add_u64 v[14:15], v[8:9], 0, v[14:15]
	v_lshlrev_b64 v[16:17], 12, v[16:17]
	v_lshlrev_b64 v[18:19], 12, v[18:19]
	v_lshlrev_b64 v[20:21], 12, v[20:21]
	v_lshlrev_b64 v[22:23], 12, v[22:23]
	v_lshl_add_u64 v[6:7], v[8:9], 0, v[6:7]
	v_lshl_add_u64 v[16:17], v[8:9], 0, v[16:17]
	v_lshl_add_u64 v[18:19], v[8:9], 0, v[18:19]
	v_lshl_add_u64 v[20:21], v[8:9], 0, v[20:21]
	v_lshl_add_u64 v[22:23], v[8:9], 0, v[22:23]
	global_load_dword v8, v[10:11], off nt
	global_load_dword v9, v[12:13], off nt
	s_nop 0
	global_load_dword v10, v[14:15], off nt
	global_load_dword v11, v[16:17], off nt
	global_load_dword v12, v[18:19], off nt
	global_load_dword v13, v[20:21], off nt
	s_nop 0
	global_load_dword v14, v[22:23], off nt
	s_nop 0
	global_load_dword v6, v[6:7], off nt
	s_waitcnt vmcnt(30)
; __device__ __forceinline__ unsigned cvtpk(float lo, float hi) { f32x2_t v = {lo, hi}; f16x2_t b = __builtin_convertvector(v, f16x2_t); return __builtin_bit_cast(unsigned, b); }
; #define LAS __attribute__((address_space(3)))
; __device__ __forceinline__ void p0_transpose_item(const float* W, const float* gain, int K, int N, bf16* WT, LAS float* scr, int item, int lane) {
;     const int nblk = N / 32, kb = item / nblk, nb = item % nblk, k0 = 64 * kb, n0 = 32 * nb;
;     float tv[32];
; #pragma unroll
;     for (int i = 0; i < 32; ++i) { const int kk = 2 * i + (lane >> 5); tv[i] = W[(size_t)(k0 + kk) * N + n0 + (lane & 31)]; }
;     if (gain) {
; #pragma unroll
;         for (int i = 0; i < 32; ++i) tv[i] *= gain[k0 + 2 * i + (lane >> 5)]; }
; #pragma unroll
;     for (int i = 0; i < 32; ++i) scr[(2 * i + (lane >> 5)) * 33 + (lane & 31)] = tv[i];
;     asm volatile("s_waitcnt lgkmcnt(0)" ::: "memory");
;     const int c = lane & 7;
; #pragma unroll
;     for (int j = 0; j < 4; ++j) { const int n = (lane >> 3) + 8 * j; const LAS float* s = scr + (8 * c) * 33 + n;
;         u32x4 o; o.x = cvtpk(s[0 * 33], s[1 * 33]); o.y = cvtpk(s[2 * 33], s[3 * 33]); o.z = cvtpk(s[4 * 33], s[5 * 33]); o.w = cvtpk(s[6 * 33], s[7 * 33]);
;         *(u32x4*)(WT + (size_t)(n0 + n) * K + k0 + 8 * c) = o; }
	ds_write2_b32 v40, v5, v26 offset1:66
	s_waitcnt vmcnt(28)
	ds_write2_b32 v40, v27, v28 offset0:132 offset1:198
	s_waitcnt vmcnt(26)
	ds_write2_b32 v46, v29, v30 offset0:8 offset1:74
	s_waitcnt vmcnt(24)
	ds_write2_b32 v46, v31, v32 offset0:140 offset1:206
	s_waitcnt vmcnt(22)
	ds_write2_b32 v47, v33, v34 offset0:16 offset1:82
	s_waitcnt vmcnt(20)
	ds_write2_b32 v47, v35, v36 offset0:148 offset1:214
	s_waitcnt vmcnt(18)
	ds_write2_b32 v48, v37, v38 offset0:24 offset1:90
	s_waitcnt vmcnt(16)
	ds_write2_b32 v48, v39, v53 offset0:156 offset1:222
	s_waitcnt vmcnt(14)
	ds_write2_b32 v49, v54, v55 offset0:32 offset1:98
	s_waitcnt vmcnt(12)
	ds_write2_b32 v49, v56, v57 offset0:164 offset1:230
	s_waitcnt vmcnt(10)
	ds_write2_b32 v50, v58, v59 offset0:40 offset1:106
	s_waitcnt vmcnt(8)
	ds_write2_b32 v50, v60, v24 offset0:172 offset1:238
	s_waitcnt vmcnt(6)
	ds_write2_b32 v51, v8, v9 offset0:48 offset1:114
	s_waitcnt vmcnt(4)
	ds_write2_b32 v51, v10, v11 offset0:180 offset1:246
	s_waitcnt vmcnt(2)
	ds_write2_b32 v52, v12, v13 offset0:56 offset1:122
	s_waitcnt vmcnt(0)
	ds_write2_b32 v52, v14, v6 offset0:188 offset1:254
	s_waitcnt lgkmcnt(0)
	s_lshl_b64 s[96:97], s[6:7], 1
	ds_read2_b32 v[10:11], v42 offset0:33 offset1:41
	ds_read2_b32 v[12:13], v42 offset1:8
	ds_read2_b32 v[14:15], v42 offset0:66 offset1:74
	ds_read2_b32 v[16:17], v42 offset0:99 offset1:107
	ds_read2_b32 v[18:19], v42 offset0:132 offset1:140
	ds_read2_b32 v[20:21], v42 offset0:165 offset1:173
	ds_read2_b32 v[22:23], v42 offset0:198 offset1:206
	ds_read2_b32 v[24:25], v42 offset0:231 offset1:239
	s_add_u32 s96, s93, s96
	s_addc_u32 s97, s94, s97
	v_mov_b32_e32 v5, v3
	v_lshl_add_u64 v[6:7], s[96:97], 0, v[4:5]
	s_mov_b64 s[96:97], 0x2000000
	v_or_b32_e32 v5, s34, v41
	v_lshl_add_u64 v[26:27], v[6:7], 0, s[96:97]
	v_lshlrev_b32_e32 v28, 13, v5
	v_mov_b32_e32 v29, v3
	s_waitcnt lgkmcnt(6)
	v_cvt_pk_f16_f32 v6, v12, v10
	s_waitcnt lgkmcnt(4)
	v_cvt_pk_f16_f32 v7, v14, v16
	s_waitcnt lgkmcnt(2)
	v_cvt_pk_f16_f32 v8, v18, v20
	s_waitcnt lgkmcnt(0)
	v_cvt_pk_f16_f32 v9, v22, v24
	v_lshl_add_u64 v[28:29], v[26:27], 0, v[28:29]
	global_store_dwordx4 v[28:29], v[6:9], off sc1
	v_or_b32_e32 v5, s34, v43
	v_lshlrev_b32_e32 v10, 13, v5
	v_cvt_pk_f16_f32 v6, v13, v11
	v_cvt_pk_f16_f32 v7, v15, v17
	v_cvt_pk_f16_f32 v8, v19, v21
	v_cvt_pk_f16_f32 v9, v23, v25
	ds_read2_b32 v[12:13], v42 offset0:49 offset1:57
	ds_read2_b32 v[14:15], v42 offset0:16 offset1:24
	ds_read2_b32 v[16:17], v42 offset0:82 offset1:90
	ds_read2_b32 v[18:19], v42 offset0:115 offset1:123
	ds_read2_b32 v[20:21], v42 offset0:148 offset1:156
	ds_read2_b32 v[22:23], v42 offset0:181 offset1:189
	ds_read2_b32 v[24:25], v42 offset0:214 offset1:222
	ds_read2_b32 v[28:29], v42 offset0:247 offset1:255
	v_mov_b32_e32 v11, v3
	v_lshl_add_u64 v[10:11], v[26:27], 0, v[10:11]
	v_or_b32_e32 v5, s34, v44
	global_store_dwordx4 v[10:11], v[6:9], off sc1
	v_lshlrev_b32_e32 v10, 13, v5
	v_mov_b32_e32 v11, v3
	s_waitcnt lgkmcnt(6)
	v_cvt_pk_f16_f32 v6, v14, v12
	s_waitcnt lgkmcnt(4)
	v_cvt_pk_f16_f32 v7, v16, v18
	s_waitcnt lgkmcnt(2)
	v_cvt_pk_f16_f32 v8, v20, v22
	s_waitcnt lgkmcnt(0)
	v_cvt_pk_f16_f32 v9, v24, v28
	v_lshl_add_u64 v[10:11], v[26:27], 0, v[10:11]
	v_or_b32_e32 v5, s34, v45
	global_store_dwordx4 v[10:11], v[6:9], off sc1
	v_lshlrev_b32_e32 v10, 13, v5
	v_mov_b32_e32 v11, v3
	v_cvt_pk_f16_f32 v6, v15, v13
	v_cvt_pk_f16_f32 v7, v17, v19
	v_cvt_pk_f16_f32 v8, v21, v23
	v_cvt_pk_f16_f32 v9, v25, v29
	v_lshl_add_u64 v[10:11], v[26:27], 0, v[10:11]
	global_store_dwordx4 v[10:11], v[6:9], off sc1
	s_waitcnt lgkmcnt(0)
	s_mov_b64 s[34:35], 0
.LBB0_16:
	s_andn2_b64 vcc, exec, s[34:35]
	s_cbranch_vccnz .LBB0_20
	s_add_i32 s6, s38, 0xe800
	s_lshl_b64 s[34:35], s[30:31], 24
	s_add_u32 s39, s22, s34
	s_addc_u32 s35, s23, s35
	s_lshr_b32 s6, s6, 1
	s_and_b32 s34, s6, 0x7fc0
	s_and_b32 s6, s44, 0xfe0
	s_lshl_b32 s95, s6, 2
	v_or_b32_e32 v5, s34, v1
	s_add_u32 s96, s39, s95
	s_addc_u32 s97, s35, 0
	v_lshlrev_b32_e32 v32, 14, v5
	v_lshl_add_u64 v[30:31], s[96:97], 0, v[2:3]
	v_mov_b32_e32 v33, v3
	v_or_b32_e32 v8, 0x8000, v32
	v_mov_b32_e32 v9, v3
	v_or_b32_e32 v10, 0x10000, v32
	v_mov_b32_e32 v11, v3
	v_or_b32_e32 v12, 0x18000, v32
	v_mov_b32_e32 v13, v3
	v_or_b32_e32 v14, 0x20000, v32
	v_mov_b32_e32 v15, v3
	v_or_b32_e32 v16, 0x28000, v32
	v_mov_b32_e32 v17, v3
	v_or_b32_e32 v18, 0x30000, v32
	v_mov_b32_e32 v19, v3
	v_or_b32_e32 v20, 0x38000, v32
	v_mov_b32_e32 v21, v3
	v_lshl_add_u64 v[6:7], v[30:31], 0, v[32:33]
	v_lshl_add_u64 v[8:9], v[30:31], 0, v[8:9]
	v_lshl_add_u64 v[10:11], v[30:31], 0, v[10:11]
	v_lshl_add_u64 v[12:13], v[30:31], 0, v[12:13]
	v_lshl_add_u64 v[14:15], v[30:31], 0, v[14:15]
	v_lshl_add_u64 v[16:17], v[30:31], 0, v[16:17]
	v_lshl_add_u64 v[18:19], v[30:31], 0, v[18:19]
	v_lshl_add_u64 v[20:21], v[30:31], 0, v[20:21]
	global_load_dword v6, v[6:7], off nt
	s_nop 0
	global_load_dword v7, v[8:9], off nt
	s_nop 0
	global_load_dword v8, v[10:11], off nt
	global_load_dword v9, v[12:13], off nt
	s_nop 0
	global_load_dword v10, v[14:15], off nt
	global_load_dword v11, v[16:17], off nt
	global_load_dword v12, v[18:19], off nt
	global_load_dword v13, v[20:21], off nt
	v_or_b32_e32 v14, 0x40000, v32
	v_mov_b32_e32 v15, v3
	v_or_b32_e32 v16, 0x48000, v32
	v_mov_b32_e32 v17, v3
	v_or_b32_e32 v18, 0x50000, v32
	v_mov_b32_e32 v19, v3
	v_or_b32_e32 v20, 0x58000, v32
	v_mov_b32_e32 v21, v3
	v_or_b32_e32 v22, 0x60000, v32
	v_mov_b32_e32 v23, v3
	v_or_b32_e32 v24, 0x68000, v32
	v_mov_b32_e32 v25, v3
	v_or_b32_e32 v26, 0x70000, v32
	v_mov_b32_e32 v27, v3
	v_or_b32_e32 v28, 0x78000, v32
	v_mov_b32_e32 v29, v3
	v_lshl_add_u64 v[14:15], v[30:31], 0, v[14:15]
; __device__ __forceinline__ void p0_transpose_item(const float* W, const float* gain, int K, int N, bf16* WT, LAS float* scr, int item, int lane) {
;     ...
;     for (int i = 0; i < 32; ++i) { const int kk = 2 * i + (lane >> 5); tv[i] = W[(size_t)(k0 + kk) * N + n0 + (lane & 31)]; }
;     if (gain) {
; #pragma unroll
;         for (int i = 0; i < 32; ++i) tv[i] *= gain[k0 + 2 * i + (lane >> 5)]; }
	v_lshl_add_u64 v[16:17], v[30:31], 0, v[16:17]
	v_lshl_add_u64 v[18:19], v[30:31], 0, v[18:19]
	v_lshl_add_u64 v[20:21], v[30:31], 0, v[20:21]
	v_lshl_add_u64 v[22:23], v[30:31], 0, v[22:23]
	v_lshl_add_u64 v[24:25], v[30:31], 0, v[24:25]
	v_lshl_add_u64 v[26:27], v[30:31], 0, v[26:27]
	v_lshl_add_u64 v[28:29], v[30:31], 0, v[28:29]
	global_load_dword v14, v[14:15], off nt
	s_nop 0
	global_load_dword v15, v[16:17], off nt
	s_nop 0
	global_load_dword v16, v[18:19], off nt
	global_load_dword v17, v[20:21], off nt
	s_nop 0
	global_load_dword v18, v[22:23], off nt
	global_load_dword v19, v[24:25], off nt
	global_load_dword v20, v[26:27], off nt
	global_load_dword v21, v[28:29], off nt
	v_or_b32_e32 v22, 0x80000, v32
	v_mov_b32_e32 v23, v3
	v_or_b32_e32 v24, 0x88000, v32
	v_mov_b32_e32 v25, v3
	v_or_b32_e32 v26, 0x90000, v32
	v_mov_b32_e32 v27, v3
	v_or_b32_e32 v28, 0x98000, v32
	v_mov_b32_e32 v29, v3
	v_or_b32_e32 v34, 0xa0000, v32
	v_mov_b32_e32 v35, v3
	v_or_b32_e32 v36, 0xa8000, v32
	v_mov_b32_e32 v37, v3
	v_lshl_add_u64 v[22:23], v[30:31], 0, v[22:23]
	v_lshl_add_u64 v[24:25], v[30:31], 0, v[24:25]
	v_lshl_add_u64 v[26:27], v[30:31], 0, v[26:27]
	v_lshl_add_u64 v[28:29], v[30:31], 0, v[28:29]
	v_lshl_add_u64 v[34:35], v[30:31], 0, v[34:35]
	v_lshl_add_u64 v[36:37], v[30:31], 0, v[36:37]
	v_or_b32_e32 v38, 0xb0000, v32
	v_mov_b32_e32 v39, v3
	v_or_b32_e32 v54, 0xb8000, v32
	v_mov_b32_e32 v55, v3
	v_lshl_add_u64 v[38:39], v[30:31], 0, v[38:39]
	v_lshl_add_u64 v[54:55], v[30:31], 0, v[54:55]
	global_load_dword v22, v[22:23], off nt
	s_nop 0
	global_load_dword v23, v[24:25], off nt
	s_nop 0
	global_load_dword v24, v[26:27], off nt
	global_load_dword v25, v[28:29], off nt
	s_nop 0
	global_load_dword v26, v[34:35], off nt
	global_load_dword v27, v[36:37], off nt
	global_load_dword v28, v[38:39], off nt
	global_load_dword v29, v[54:55], off nt
	v_or_b32_e32 v34, 0xc0000, v32
	v_mov_b32_e32 v35, v3
	v_or_b32_e32 v36, 0xc8000, v32
	v_mov_b32_e32 v37, v3
	v_lshl_add_u64 v[34:35], v[30:31], 0, v[34:35]
	v_lshl_add_u64 v[36:37], v[30:31], 0, v[36:37]
	v_or_b32_e32 v38, 0xd0000, v32
	v_mov_b32_e32 v39, v3
	v_or_b32_e32 v54, 0xd8000, v32
	v_mov_b32_e32 v55, v3
	v_or_b32_e32 v56, 0xe0000, v32
	v_mov_b32_e32 v57, v3
	v_or_b32_e32 v58, 0xe8000, v32
	v_mov_b32_e32 v59, v3
	v_or_b32_e32 v60, 0xf0000, v32
	v_mov_b32_e32 v61, v3
	v_or_b32_e32 v32, 0xf8000, v32
	v_lshl_add_u64 v[38:39], v[30:31], 0, v[38:39]
	v_lshl_add_u64 v[54:55], v[30:31], 0, v[54:55]
	v_lshl_add_u64 v[56:57], v[30:31], 0, v[56:57]
	v_lshl_add_u64 v[58:59], v[30:31], 0, v[58:59]
	v_lshl_add_u64 v[60:61], v[30:31], 0, v[60:61]
	v_lshl_add_u64 v[62:63], v[30:31], 0, v[32:33]
	global_load_dword v30, v[34:35], off nt
	global_load_dword v31, v[36:37], off nt
	global_load_dword v32, v[38:39], off nt
	global_load_dword v33, v[54:55], off nt
	s_nop 0
	global_load_dword v36, v[56:57], off nt
	global_load_dword v37, v[58:59], off nt
	global_load_dword v34, v[60:61], off nt
	global_load_dword v35, v[62:63], off nt
	s_andn2_b64 vcc, exec, s[26:27]
	s_cbranch_vccnz .LBB0_19
	s_lshl_b32 s96, s30, 10
	s_ashr_i32 s97, s96, 31
	s_lshl_b64 s[96:97], s[96:97], 2
	s_add_u32 s96, s20, s96
	s_addc_u32 s97, s21, s97
	v_lshlrev_b32_e32 v5, 2, v5
	global_load_dword v38, v5, s[96:97] nt
	global_load_dword v39, v5, s[96:97] offset:8 nt
	global_load_dword v54, v5, s[96:97] offset:16 nt
	global_load_dword v55, v5, s[96:97] offset:24 nt
	global_load_dword v56, v5, s[96:97] offset:32 nt
	global_load_dword v57, v5, s[96:97] offset:40 nt
	global_load_dword v58, v5, s[96:97] offset:48 nt
	global_load_dword v59, v5, s[96:97] offset:56 nt
	global_load_dword v60, v5, s[96:97] offset:64 nt
	global_load_dword v61, v5, s[96:97] offset:72 nt
	global_load_dword v62, v5, s[96:97] offset:80 nt
	global_load_dword v63, v5, s[96:97] offset:88 nt
	global_load_dword v64, v5, s[96:97] offset:96 nt
	global_load_dword v65, v5, s[96:97] offset:104 nt
	global_load_dword v66, v5, s[96:97] offset:112 nt
	global_load_dword v67, v5, s[96:97] offset:120 nt
	global_load_dword v68, v5, s[96:97] offset:128 nt
	global_load_dword v69, v5, s[96:97] offset:136 nt
	global_load_dword v70, v5, s[96:97] offset:144 nt
	global_load_dword v71, v5, s[96:97] offset:152 nt
	global_load_dword v72, v5, s[96:97] offset:160 nt
	global_load_dword v73, v5, s[96:97] offset:168 nt
	global_load_dword v74, v5, s[96:97] offset:176 nt
	global_load_dword v75, v5, s[96:97] offset:184 nt
	global_load_dword v76, v5, s[96:97] offset:192 nt
	global_load_dword v77, v5, s[96:97] offset:200 nt
	global_load_dword v78, v5, s[96:97] offset:208 nt
	global_load_dword v79, v5, s[96:97] offset:216 nt
	global_load_dword v80, v5, s[96:97] offset:224 nt
	global_load_dword v81, v5, s[96:97] offset:232 nt
	global_load_dword v82, v5, s[96:97] offset:240 nt
	global_load_dword v83, v5, s[96:97] offset:248 nt
	s_waitcnt vmcnt(30)
	v_pk_mul_f32 v[6:7], v[6:7], v[38:39]
	s_waitcnt vmcnt(28)
	v_pk_mul_f32 v[8:9], v[8:9], v[54:55]
	s_waitcnt vmcnt(26)
	v_pk_mul_f32 v[10:11], v[10:11], v[56:57]
	s_waitcnt vmcnt(24)
	v_pk_mul_f32 v[12:13], v[12:13], v[58:59]
	s_waitcnt vmcnt(22)
	v_pk_mul_f32 v[14:15], v[14:15], v[60:61]
	s_waitcnt vmcnt(20)
	v_pk_mul_f32 v[16:17], v[16:17], v[62:63]
	s_waitcnt vmcnt(18)
	v_pk_mul_f32 v[18:19], v[18:19], v[64:65]
	s_waitcnt vmcnt(16)
	v_pk_mul_f32 v[20:21], v[20:21], v[66:67]
	s_waitcnt vmcnt(14)
	v_pk_mul_f32 v[22:23], v[22:23], v[68:69]
	s_waitcnt vmcnt(12)
	v_pk_mul_f32 v[24:25], v[24:25], v[70:71]
	s_waitcnt vmcnt(10)
	v_pk_mul_f32 v[26:27], v[26:27], v[72:73]
	s_waitcnt vmcnt(8)
	v_pk_mul_f32 v[28:29], v[28:29], v[74:75]
	s_waitcnt vmcnt(6)
	v_pk_mul_f32 v[30:31], v[30:31], v[76:77]
	s_waitcnt vmcnt(4)
	v_pk_mul_f32 v[32:33], v[32:33], v[78:79]
	s_waitcnt vmcnt(2)
	v_pk_mul_f32 v[36:37], v[36:37], v[80:81]
	s_waitcnt vmcnt(0)
	v_pk_mul_f32 v[34:35], v[34:35], v[82:83]

; __device__ __forceinline__ void p0_transpose_item(const float* W, const float* gain, int K, int N, bf16* WT, LAS float* scr, int item, int lane) {
;     const int nblk = N / 32, kb = item / nblk, nb = item % nblk, k0 = 64 * kb, n0 = 32 * nb;
;     float tv[32];
; #pragma unroll
;     for (int i = 0; i < 32; ++i) { const int kk = 2 * i + (lane >> 5); tv[i] = W[(size_t)(k0 + kk) * N + n0 + (lane & 31)]; }
.LBB0_21:
	s_andn2_b64 vcc, exec, s[34:35]
	s_cbranch_vccnz .LBB0_23
	s_lshl_b64 s[34:35], s[30:31], 22
	s_add_u32 s39, s18, s34
	s_mul_i32 s6, s30, 0xffffb000
	s_addc_u32 s35, s19, s35
	s_add_i32 s6, s46, s6
	s_add_i32 s6, s6, 0x1d400
	s_and_b32 s34, s6, 0x1ffc0
	s_and_b32 s6, s44, 0x3e0
	s_lshl_b32 s95, s6, 2
	s_add_u32 s96, s39, s95
	v_or_b32_e32 v5, s34, v1
	s_addc_u32 s97, s35, 0
	v_lshl_add_u64 v[6:7], s[96:97], 0, v[2:3]
	v_lshlrev_b32_e32 v8, 12, v5
	v_mov_b32_e32 v9, v3
	v_lshl_add_u64 v[6:7], v[6:7], 0, v[8:9]
	v_add_co_u32_e32 v8, vcc, s55, v6
	s_lshl_b32 s34, s34, 1
	s_nop 0
	v_addc_co_u32_e32 v9, vcc, 0, v7, vcc
	v_add_co_u32_e32 v10, vcc, s68, v6
	s_add_u32 s34, s93, s34
	s_nop 0
	v_addc_co_u32_e32 v11, vcc, 0, v7, vcc
	v_add_co_u32_e32 v12, vcc, s69, v6
	s_addc_u32 s35, s94, 0
	s_nop 0
	v_addc_co_u32_e32 v13, vcc, 0, v7, vcc
	v_add_co_u32_e32 v14, vcc, s48, v6
	s_nop 1
	v_addc_co_u32_e32 v15, vcc, 0, v7, vcc
	v_add_co_u32_e32 v16, vcc, s70, v6
	s_nop 1
	v_addc_co_u32_e32 v17, vcc, 0, v7, vcc
	v_add_co_u32_e32 v18, vcc, s71, v6
	s_nop 1
	v_addc_co_u32_e32 v19, vcc, 0, v7, vcc
	v_add_co_u32_e32 v20, vcc, s72, v6
	s_nop 1
	v_addc_co_u32_e32 v21, vcc, 0, v7, vcc
	global_load_dword v5, v[6:7], off nt
	global_load_dword v24, v[8:9], off nt
	global_load_dword v25, v[10:11], off nt
	global_load_dword v26, v[12:13], off nt
	global_load_dword v27, v[14:15], off nt
	global_load_dword v28, v[16:17], off nt
	global_load_dword v29, v[18:19], off nt
	global_load_dword v30, v[20:21], off nt
	v_add_co_u32_e32 v8, vcc, s49, v6
	s_nop 1
	v_addc_co_u32_e32 v9, vcc, 0, v7, vcc
	v_add_co_u32_e32 v10, vcc, s73, v6
	s_nop 1
	v_addc_co_u32_e32 v11, vcc, 0, v7, vcc
	v_add_co_u32_e32 v12, vcc, s74, v6
	s_nop 1
	v_addc_co_u32_e32 v13, vcc, 0, v7, vcc
	v_add_co_u32_e32 v14, vcc, s75, v6
	s_nop 1
	v_addc_co_u32_e32 v15, vcc, 0, v7, vcc
	v_add_co_u32_e32 v16, vcc, s2, v6
	s_nop 1
	v_addc_co_u32_e32 v17, vcc, 0, v7, vcc
	v_add_co_u32_e32 v18, vcc, s76, v6
	s_nop 1
	v_addc_co_u32_e32 v19, vcc, 0, v7, vcc
	v_add_co_u32_e32 v20, vcc, s77, v6
	s_nop 1
	v_addc_co_u32_e32 v21, vcc, 0, v7, vcc
	v_add_co_u32_e32 v22, vcc, s78, v6
	s_nop 1
	v_addc_co_u32_e32 v23, vcc, 0, v7, vcc
	global_load_dword v31, v[8:9], off nt
	global_load_dword v32, v[10:11], off nt
	global_load_dword v33, v[12:13], off nt
	global_load_dword v34, v[14:15], off nt
	global_load_dword v35, v[16:17], off nt
	global_load_dword v36, v[18:19], off nt
	global_load_dword v37, v[20:21], off nt
	global_load_dword v38, v[22:23], off nt
	v_add_co_u32_e32 v8, vcc, s3, v6
	s_nop 1
	v_addc_co_u32_e32 v9, vcc, 0, v7, vcc
	v_add_co_u32_e32 v10, vcc, s79, v6
	s_nop 1
	v_addc_co_u32_e32 v11, vcc, 0, v7, vcc
	v_add_co_u32_e32 v12, vcc, s80, v6
	s_nop 1
	v_addc_co_u32_e32 v13, vcc, 0, v7, vcc
	v_add_co_u32_e32 v14, vcc, s81, v6
	s_nop 1
	v_addc_co_u32_e32 v15, vcc, 0, v7, vcc
	v_add_co_u32_e32 v16, vcc, s52, v6
	s_nop 1
	v_addc_co_u32_e32 v17, vcc, 0, v7, vcc
	v_add_co_u32_e32 v18, vcc, s82, v6
	s_nop 1
	v_addc_co_u32_e32 v19, vcc, 0, v7, vcc
	v_add_co_u32_e32 v20, vcc, s83, v6
	s_nop 1
	v_addc_co_u32_e32 v21, vcc, 0, v7, vcc
	v_add_co_u32_e32 v22, vcc, s84, v6
	s_nop 1
	v_addc_co_u32_e32 v23, vcc, 0, v7, vcc
	global_load_dword v39, v[8:9], off nt
	global_load_dword v53, v[10:11], off nt
	global_load_dword v54, v[12:13], off nt
	global_load_dword v55, v[14:15], off nt
	global_load_dword v56, v[16:17], off nt
	global_load_dword v57, v[18:19], off nt
	global_load_dword v58, v[20:21], off nt
	s_nop 0
	global_load_dword v22, v[22:23], off nt
	v_add_co_u32_e32 v8, vcc, s53, v6
	s_nop 1
	v_addc_co_u32_e32 v9, vcc, 0, v7, vcc
	v_add_co_u32_e32 v10, vcc, s85, v6
	s_nop 1
	v_addc_co_u32_e32 v11, vcc, 0, v7, vcc
	v_add_co_u32_e32 v12, vcc, s86, v6
	s_nop 1
	v_addc_co_u32_e32 v13, vcc, 0, v7, vcc
	v_add_co_u32_e32 v14, vcc, s87, v6
	s_nop 1
	v_addc_co_u32_e32 v15, vcc, 0, v7, vcc
	v_add_co_u32_e32 v16, vcc, s54, v6
	s_nop 1
	v_addc_co_u32_e32 v17, vcc, 0, v7, vcc
	v_add_co_u32_e32 v18, vcc, s88, v6
	s_nop 1
	v_addc_co_u32_e32 v19, vcc, 0, v7, vcc
	v_add_co_u32_e32 v20, vcc, s89, v6
	s_nop 1
	v_addc_co_u32_e32 v21, vcc, 0, v7, vcc
	v_add_co_u32_e32 v6, vcc, s90, v6
	s_nop 1
	v_addc_co_u32_e32 v7, vcc, 0, v7, vcc
	global_load_dword v8, v[8:9], off nt
	s_nop 0
	global_load_dword v9, v[10:11], off nt
	s_nop 0
	global_load_dword v10, v[12:13], off nt
	global_load_dword v11, v[14:15], off nt
	s_nop 0
	global_load_dword v12, v[16:17], off nt
	global_load_dword v13, v[18:19], off nt
	global_load_dword v14, v[20:21], off nt
	s_nop 0
	global_load_dword v6, v[6:7], off nt
	s_waitcnt vmcnt(30)
; __device__ __forceinline__ unsigned cvtpk(float lo, float hi) { f32x2_t v = {lo, hi}; f16x2_t b = __builtin_convertvector(v, f16x2_t); return __builtin_bit_cast(unsigned, b); }
; #define LAS __attribute__((address_space(3)))
; __device__ __forceinline__ void p0_transpose_item(const float* W, const float* gain, int K, int N, bf16* WT, LAS float* scr, int item, int lane) {
;     ...
;     for (int i = 0; i < 32; ++i) scr[(2 * i + (lane >> 5)) * 33 + (lane & 31)] = tv[i];
;     asm volatile("s_waitcnt lgkmcnt(0)" ::: "memory");
;     const int c = lane & 7;
; #pragma unroll
;     for (int j = 0; j < 4; ++j) { const int n = (lane >> 3) + 8 * j; const LAS float* s = scr + (8 * c) * 33 + n;
;         u32x4 o; o.x = cvtpk(s[0 * 33], s[1 * 33]); o.y = cvtpk(s[2 * 33], s[3 * 33]); o.z = cvtpk(s[4 * 33], s[5 * 33]); o.w = cvtpk(s[6 * 33], s[7 * 33]);
;         *(u32x4*)(WT + (size_t)(n0 + n) * K + k0 + 8 * c) = o; }
	ds_write2_b32 v40, v5, v24 offset1:66
	s_waitcnt vmcnt(28)
	ds_write2_b32 v40, v25, v26 offset0:132 offset1:198
	s_waitcnt vmcnt(26)
	ds_write2_b32 v46, v27, v28 offset0:8 offset1:74
	s_waitcnt vmcnt(24)
	ds_write2_b32 v46, v29, v30 offset0:140 offset1:206
	s_waitcnt vmcnt(22)
	ds_write2_b32 v47, v31, v32 offset0:16 offset1:82
	s_waitcnt vmcnt(20)
	ds_write2_b32 v47, v33, v34 offset0:148 offset1:214
	s_waitcnt vmcnt(18)
	ds_write2_b32 v48, v35, v36 offset0:24 offset1:90
	s_waitcnt vmcnt(16)
	ds_write2_b32 v48, v37, v38 offset0:156 offset1:222
	s_waitcnt vmcnt(14)
	ds_write2_b32 v49, v39, v53 offset0:32 offset1:98
	s_waitcnt vmcnt(12)
	ds_write2_b32 v49, v54, v55 offset0:164 offset1:230
	s_waitcnt vmcnt(10)
	ds_write2_b32 v50, v56, v57 offset0:40 offset1:106
	s_waitcnt vmcnt(8)
	ds_write2_b32 v50, v58, v22 offset0:172 offset1:238
	s_waitcnt vmcnt(6)
	ds_write2_b32 v51, v8, v9 offset0:48 offset1:114
	s_waitcnt vmcnt(4)
	ds_write2_b32 v51, v10, v11 offset0:180 offset1:246
	s_waitcnt vmcnt(2)
	ds_write2_b32 v52, v12, v13 offset0:56 offset1:122
	s_waitcnt vmcnt(0)
	ds_write2_b32 v52, v14, v6 offset0:188 offset1:254
	s_waitcnt lgkmcnt(0)
	ds_read2_b32 v[10:11], v42 offset0:33 offset1:41
	ds_read2_b32 v[12:13], v42 offset1:8
	ds_read2_b32 v[14:15], v42 offset0:66 offset1:74
	ds_read2_b32 v[16:17], v42 offset0:99 offset1:107
	ds_read2_b32 v[18:19], v42 offset0:132 offset1:140
	ds_read2_b32 v[20:21], v42 offset0:165 offset1:173
	ds_read2_b32 v[22:23], v42 offset0:198 offset1:206
	ds_read2_b32 v[24:25], v42 offset0:231 offset1:239
	v_mov_b32_e32 v5, v3
	v_lshl_add_u64 v[6:7], s[34:35], 0, v[4:5]
	s_mov_b64 s[34:35], 0x1600000
	v_or_b32_e32 v5, s6, v41
	v_lshl_add_u64 v[26:27], v[6:7], 0, s[34:35]
	v_lshlrev_b32_e32 v28, 11, v5
	v_mov_b32_e32 v29, v3
	s_waitcnt lgkmcnt(6)
	v_cvt_pk_f16_f32 v6, v12, v10
	s_waitcnt lgkmcnt(4)
	v_cvt_pk_f16_f32 v7, v14, v16
	s_waitcnt lgkmcnt(2)
	v_cvt_pk_f16_f32 v8, v18, v20
	s_waitcnt lgkmcnt(0)
	v_cvt_pk_f16_f32 v9, v22, v24
	v_lshl_add_u64 v[28:29], v[26:27], 0, v[28:29]
	global_store_dwordx4 v[28:29], v[6:9], off sc1
	v_or_b32_e32 v5, s6, v43
	v_lshlrev_b32_e32 v10, 11, v5
	v_cvt_pk_f16_f32 v6, v13, v11
	v_cvt_pk_f16_f32 v7, v15, v17
	v_cvt_pk_f16_f32 v8, v19, v21
	v_cvt_pk_f16_f32 v9, v23, v25
	ds_read2_b32 v[12:13], v42 offset0:49 offset1:57
	ds_read2_b32 v[14:15], v42 offset0:16 offset1:24
	ds_read2_b32 v[16:17], v42 offset0:82 offset1:90
	ds_read2_b32 v[18:19], v42 offset0:115 offset1:123
	ds_read2_b32 v[20:21], v42 offset0:148 offset1:156
	ds_read2_b32 v[22:23], v42 offset0:181 offset1:189
	ds_read2_b32 v[24:25], v42 offset0:214 offset1:222
	ds_read2_b32 v[28:29], v42 offset0:247 offset1:255
	v_mov_b32_e32 v11, v3
	v_lshl_add_u64 v[10:11], v[26:27], 0, v[10:11]
	v_or_b32_e32 v5, s6, v44
	global_store_dwordx4 v[10:11], v[6:9], off sc1
	v_lshlrev_b32_e32 v10, 11, v5
	v_mov_b32_e32 v11, v3
	s_waitcnt lgkmcnt(6)
	v_cvt_pk_f16_f32 v6, v14, v12
	s_waitcnt lgkmcnt(4)
	v_cvt_pk_f16_f32 v7, v16, v18
	s_waitcnt lgkmcnt(2)
	v_cvt_pk_f16_f32 v8, v20, v22
	s_waitcnt lgkmcnt(0)
	v_cvt_pk_f16_f32 v9, v24, v28
	v_lshl_add_u64 v[10:11], v[26:27], 0, v[10:11]
	v_or_b32_e32 v5, s6, v45
	global_store_dwordx4 v[10:11], v[6:9], off sc1
	v_lshlrev_b32_e32 v10, 11, v5
	v_mov_b32_e32 v11, v3
	v_cvt_pk_f16_f32 v6, v15, v13
	v_cvt_pk_f16_f32 v7, v17, v19
	v_cvt_pk_f16_f32 v8, v21, v23
	v_cvt_pk_f16_f32 v9, v25, v29
	v_lshl_add_u64 v[10:11], v[26:27], 0, v[10:11]
	global_store_dwordx4 v[10:11], v[6:9], off sc1
	s_waitcnt lgkmcnt(0)

; __device__ __forceinline__ void p0_transpose_item(const float* W, const float* gain, int K, int N, bf16* WT, LAS float* scr, int item, int lane) {
;     const int nblk = N / 32, kb = item / nblk, nb = item % nblk, k0 = 64 * kb, n0 = 32 * nb;
;     float tv[32];
; #pragma unroll
;     for (int i = 0; i < 32; ++i) { const int kk = 2 * i + (lane >> 5); tv[i] = W[(size_t)(k0 + kk) * N + n0 + (lane & 31)]; }
.LBB0_24:
	s_andn2_b64 vcc, exec, s[34:35]
	s_cbranch_vccnz .LBB0_26
	s_lshl_b64 s[34:35], s[30:31], 22
	s_add_u32 s39, s16, s34
	s_mul_i32 s6, s30, 0xffffb000
	s_addc_u32 s35, s17, s35
	s_add_i32 s6, s46, s6
	s_add_i32 s6, s6, 0x1d800
	s_and_b32 s34, s6, 0x1ffc0
	s_and_b32 s6, s44, 0x3e0
	s_lshl_b32 s95, s6, 2
	s_add_u32 s96, s39, s95
	v_or_b32_e32 v5, s34, v1
	s_addc_u32 s97, s35, 0
	v_lshl_add_u64 v[6:7], s[96:97], 0, v[2:3]
	v_lshlrev_b32_e32 v8, 12, v5
	v_mov_b32_e32 v9, v3
	v_lshl_add_u64 v[6:7], v[6:7], 0, v[8:9]
	v_add_co_u32_e32 v8, vcc, s55, v6
	s_lshl_b32 s34, s34, 1
	s_nop 0
	v_addc_co_u32_e32 v9, vcc, 0, v7, vcc
	v_add_co_u32_e32 v10, vcc, s68, v6
	s_add_u32 s34, s93, s34
	s_nop 0
	v_addc_co_u32_e32 v11, vcc, 0, v7, vcc
	v_add_co_u32_e32 v12, vcc, s69, v6
	s_addc_u32 s35, s94, 0
	s_nop 0
	v_addc_co_u32_e32 v13, vcc, 0, v7, vcc
	v_add_co_u32_e32 v14, vcc, s48, v6
	s_nop 1
	v_addc_co_u32_e32 v15, vcc, 0, v7, vcc
	v_add_co_u32_e32 v16, vcc, s70, v6
	s_nop 1
	v_addc_co_u32_e32 v17, vcc, 0, v7, vcc
	v_add_co_u32_e32 v18, vcc, s71, v6
	s_nop 1
	v_addc_co_u32_e32 v19, vcc, 0, v7, vcc
	v_add_co_u32_e32 v20, vcc, s72, v6
	s_nop 1
	v_addc_co_u32_e32 v21, vcc, 0, v7, vcc
	global_load_dword v5, v[6:7], off nt
	global_load_dword v24, v[8:9], off nt
	global_load_dword v25, v[10:11], off nt
	global_load_dword v26, v[12:13], off nt
	global_load_dword v27, v[14:15], off nt
	global_load_dword v28, v[16:17], off nt
	global_load_dword v29, v[18:19], off nt
	global_load_dword v30, v[20:21], off nt
	v_add_co_u32_e32 v8, vcc, s49, v6
	s_nop 1
	v_addc_co_u32_e32 v9, vcc, 0, v7, vcc
	v_add_co_u32_e32 v10, vcc, s73, v6
	s_nop 1
	v_addc_co_u32_e32 v11, vcc, 0, v7, vcc
	v_add_co_u32_e32 v12, vcc, s74, v6
	s_nop 1
	v_addc_co_u32_e32 v13, vcc, 0, v7, vcc
	v_add_co_u32_e32 v14, vcc, s75, v6
	s_nop 1
	v_addc_co_u32_e32 v15, vcc, 0, v7, vcc
	v_add_co_u32_e32 v16, vcc, s2, v6
	s_nop 1
	v_addc_co_u32_e32 v17, vcc, 0, v7, vcc
	v_add_co_u32_e32 v18, vcc, s76, v6
	s_nop 1
	v_addc_co_u32_e32 v19, vcc, 0, v7, vcc
	v_add_co_u32_e32 v20, vcc, s77, v6
	s_nop 1
	v_addc_co_u32_e32 v21, vcc, 0, v7, vcc
	v_add_co_u32_e32 v22, vcc, s78, v6
	s_nop 1
	v_addc_co_u32_e32 v23, vcc, 0, v7, vcc
	global_load_dword v31, v[8:9], off nt
	global_load_dword v32, v[10:11], off nt
	global_load_dword v33, v[12:13], off nt
	global_load_dword v34, v[14:15], off nt
	global_load_dword v35, v[16:17], off nt
	global_load_dword v36, v[18:19], off nt
	global_load_dword v37, v[20:21], off nt
	global_load_dword v38, v[22:23], off nt
	v_add_co_u32_e32 v8, vcc, s3, v6
	s_nop 1
	v_addc_co_u32_e32 v9, vcc, 0, v7, vcc
	v_add_co_u32_e32 v10, vcc, s79, v6
	s_nop 1
	v_addc_co_u32_e32 v11, vcc, 0, v7, vcc
	v_add_co_u32_e32 v12, vcc, s80, v6
	s_nop 1
	v_addc_co_u32_e32 v13, vcc, 0, v7, vcc
	v_add_co_u32_e32 v14, vcc, s81, v6
	s_nop 1
	v_addc_co_u32_e32 v15, vcc, 0, v7, vcc
	v_add_co_u32_e32 v16, vcc, s52, v6
	s_nop 1
	v_addc_co_u32_e32 v17, vcc, 0, v7, vcc
	v_add_co_u32_e32 v18, vcc, s82, v6
	s_nop 1
	v_addc_co_u32_e32 v19, vcc, 0, v7, vcc
	v_add_co_u32_e32 v20, vcc, s83, v6
	s_nop 1
	v_addc_co_u32_e32 v21, vcc, 0, v7, vcc
	v_add_co_u32_e32 v22, vcc, s84, v6
	s_nop 1
	v_addc_co_u32_e32 v23, vcc, 0, v7, vcc
	global_load_dword v39, v[8:9], off nt
	global_load_dword v53, v[10:11], off nt
	global_load_dword v54, v[12:13], off nt
	global_load_dword v55, v[14:15], off nt
	global_load_dword v56, v[16:17], off nt
	global_load_dword v57, v[18:19], off nt
	global_load_dword v58, v[20:21], off nt
	s_nop 0
	global_load_dword v22, v[22:23], off nt
	v_add_co_u32_e32 v8, vcc, s53, v6
	s_nop 1
	v_addc_co_u32_e32 v9, vcc, 0, v7, vcc
	v_add_co_u32_e32 v10, vcc, s85, v6
	s_nop 1
	v_addc_co_u32_e32 v11, vcc, 0, v7, vcc
	v_add_co_u32_e32 v12, vcc, s86, v6
	s_nop 1
	v_addc_co_u32_e32 v13, vcc, 0, v7, vcc
	v_add_co_u32_e32 v14, vcc, s87, v6
	s_nop 1
	v_addc_co_u32_e32 v15, vcc, 0, v7, vcc
	v_add_co_u32_e32 v16, vcc, s54, v6
	s_nop 1
	v_addc_co_u32_e32 v17, vcc, 0, v7, vcc
	v_add_co_u32_e32 v18, vcc, s88, v6
	s_nop 1
	v_addc_co_u32_e32 v19, vcc, 0, v7, vcc
	v_add_co_u32_e32 v20, vcc, s89, v6
	s_nop 1
	v_addc_co_u32_e32 v21, vcc, 0, v7, vcc
	v_add_co_u32_e32 v6, vcc, s90, v6
	s_nop 1
	v_addc_co_u32_e32 v7, vcc, 0, v7, vcc
	global_load_dword v8, v[8:9], off nt
	s_nop 0
	global_load_dword v9, v[10:11], off nt
	s_nop 0
	global_load_dword v10, v[12:13], off nt
	global_load_dword v11, v[14:15], off nt
	s_nop 0
	global_load_dword v12, v[16:17], off nt
	global_load_dword v13, v[18:19], off nt
	global_load_dword v14, v[20:21], off nt
	s_nop 0
	global_load_dword v6, v[6:7], off nt
	s_waitcnt vmcnt(30)
; __device__ __forceinline__ unsigned cvtpk(float lo, float hi) { f32x2_t v = {lo, hi}; f16x2_t b = __builtin_convertvector(v, f16x2_t); return __builtin_bit_cast(unsigned, b); }
; #define LAS __attribute__((address_space(3)))
; __device__ __forceinline__ void p0_transpose_item(const float* W, const float* gain, int K, int N, bf16* WT, LAS float* scr, int item, int lane) {
;     ...
;     for (int i = 0; i < 32; ++i) scr[(2 * i + (lane >> 5)) * 33 + (lane & 31)] = tv[i];
;     asm volatile("s_waitcnt lgkmcnt(0)" ::: "memory");
;     const int c = lane & 7;
; #pragma unroll
;     for (int j = 0; j < 4; ++j) { const int n = (lane >> 3) + 8 * j; const LAS float* s = scr + (8 * c) * 33 + n;
;         u32x4 o; o.x = cvtpk(s[0 * 33], s[1 * 33]); o.y = cvtpk(s[2 * 33], s[3 * 33]); o.z = cvtpk(s[4 * 33], s[5 * 33]); o.w = cvtpk(s[6 * 33], s[7 * 33]);
;         *(u32x4*)(WT + (size_t)(n0 + n) * K + k0 + 8 * c) = o; }
	ds_write2_b32 v40, v5, v24 offset1:66
	s_waitcnt vmcnt(28)
	ds_write2_b32 v40, v25, v26 offset0:132 offset1:198
	s_waitcnt vmcnt(26)
	ds_write2_b32 v46, v27, v28 offset0:8 offset1:74
	s_waitcnt vmcnt(24)
	ds_write2_b32 v46, v29, v30 offset0:140 offset1:206
	s_waitcnt vmcnt(22)
	ds_write2_b32 v47, v31, v32 offset0:16 offset1:82
	s_waitcnt vmcnt(20)
	ds_write2_b32 v47, v33, v34 offset0:148 offset1:214
	s_waitcnt vmcnt(18)
	ds_write2_b32 v48, v35, v36 offset0:24 offset1:90
	s_waitcnt vmcnt(16)
	ds_write2_b32 v48, v37, v38 offset0:156 offset1:222
	s_waitcnt vmcnt(14)
	ds_write2_b32 v49, v39, v53 offset0:32 offset1:98
	s_waitcnt vmcnt(12)
	ds_write2_b32 v49, v54, v55 offset0:164 offset1:230
	s_waitcnt vmcnt(10)
	ds_write2_b32 v50, v56, v57 offset0:40 offset1:106
	s_waitcnt vmcnt(8)
	ds_write2_b32 v50, v58, v22 offset0:172 offset1:238
	s_waitcnt vmcnt(6)
	ds_write2_b32 v51, v8, v9 offset0:48 offset1:114
	s_waitcnt vmcnt(4)
	ds_write2_b32 v51, v10, v11 offset0:180 offset1:246
	s_waitcnt vmcnt(2)
	ds_write2_b32 v52, v12, v13 offset0:56 offset1:122
	s_waitcnt vmcnt(0)
	ds_write2_b32 v52, v14, v6 offset0:188 offset1:254
	s_waitcnt lgkmcnt(0)
	ds_read2_b32 v[10:11], v42 offset0:33 offset1:41
	ds_read2_b32 v[12:13], v42 offset1:8
	ds_read2_b32 v[14:15], v42 offset0:66 offset1:74
	ds_read2_b32 v[16:17], v42 offset0:99 offset1:107
	ds_read2_b32 v[18:19], v42 offset0:132 offset1:140
	ds_read2_b32 v[20:21], v42 offset0:165 offset1:173
	ds_read2_b32 v[22:23], v42 offset0:198 offset1:206
	ds_read2_b32 v[24:25], v42 offset0:231 offset1:239
	v_mov_b32_e32 v5, v3
	v_lshl_add_u64 v[6:7], s[34:35], 0, v[4:5]
	v_or_b32_e32 v5, s6, v41
	v_lshl_add_u64 v[26:27], v[6:7], 0, s[0:1]
	v_lshlrev_b32_e32 v28, 11, v5
	v_mov_b32_e32 v29, v3
	s_waitcnt lgkmcnt(6)
	v_cvt_pk_f16_f32 v6, v12, v10
	s_waitcnt lgkmcnt(4)
	v_cvt_pk_f16_f32 v7, v14, v16
	s_waitcnt lgkmcnt(2)
	v_cvt_pk_f16_f32 v8, v18, v20
	s_waitcnt lgkmcnt(0)
	v_cvt_pk_f16_f32 v9, v22, v24
	v_lshl_add_u64 v[28:29], v[26:27], 0, v[28:29]
	global_store_dwordx4 v[28:29], v[6:9], off sc1
	v_or_b32_e32 v5, s6, v43
	v_lshlrev_b32_e32 v10, 11, v5
	v_cvt_pk_f16_f32 v6, v13, v11
	v_cvt_pk_f16_f32 v7, v15, v17
	v_cvt_pk_f16_f32 v8, v19, v21
	v_cvt_pk_f16_f32 v9, v23, v25
	ds_read2_b32 v[12:13], v42 offset0:49 offset1:57
	ds_read2_b32 v[14:15], v42 offset0:16 offset1:24
	ds_read2_b32 v[16:17], v42 offset0:82 offset1:90
	ds_read2_b32 v[18:19], v42 offset0:115 offset1:123
	ds_read2_b32 v[20:21], v42 offset0:148 offset1:156
	ds_read2_b32 v[22:23], v42 offset0:181 offset1:189
	ds_read2_b32 v[24:25], v42 offset0:214 offset1:222
	ds_read2_b32 v[28:29], v42 offset0:247 offset1:255
	v_mov_b32_e32 v11, v3
	v_lshl_add_u64 v[10:11], v[26:27], 0, v[10:11]
	v_or_b32_e32 v5, s6, v44
	global_store_dwordx4 v[10:11], v[6:9], off sc1
	v_lshlrev_b32_e32 v10, 11, v5
	v_mov_b32_e32 v11, v3
	s_waitcnt lgkmcnt(6)
	v_cvt_pk_f16_f32 v6, v14, v12
	s_waitcnt lgkmcnt(4)
	v_cvt_pk_f16_f32 v7, v16, v18
	s_waitcnt lgkmcnt(2)
	v_cvt_pk_f16_f32 v8, v20, v22
	s_waitcnt lgkmcnt(0)
	v_cvt_pk_f16_f32 v9, v24, v28
	v_lshl_add_u64 v[10:11], v[26:27], 0, v[10:11]
	v_or_b32_e32 v5, s6, v45
	global_store_dwordx4 v[10:11], v[6:9], off sc1
	v_lshlrev_b32_e32 v10, 11, v5
	v_mov_b32_e32 v11, v3
	v_cvt_pk_f16_f32 v6, v15, v13
	v_cvt_pk_f16_f32 v7, v17, v19
	v_cvt_pk_f16_f32 v8, v21, v23
	v_cvt_pk_f16_f32 v9, v25, v29
	v_lshl_add_u64 v[10:11], v[26:27], 0, v[10:11]
	global_store_dwordx4 v[10:11], v[6:9], off sc1
	s_waitcnt lgkmcnt(0)

; __device__ __forceinline__ void p0_transpose_item(const float* W, const float* gain, int K, int N, bf16* WT, LAS float* scr, int item, int lane) {
;     const int nblk = N / 32, kb = item / nblk, nb = item % nblk, k0 = 64 * kb, n0 = 32 * nb;
;     float tv[32];
; #pragma unroll
;     for (int i = 0; i < 32; ++i) { const int kk = 2 * i + (lane >> 5); tv[i] = W[(size_t)(k0 + kk) * N + n0 + (lane & 31)]; }
.LBB0_27:
	s_andn2_b64 vcc, exec, s[34:35]
	s_cbranch_vccnz .LBB0_29
	s_lshl_b64 s[34:35], s[30:31], 21
	s_add_u32 s34, s14, s34
	s_addc_u32 s35, s15, s35
	s_and_b32 s6, s44, 0x3e0
	s_and_b32 s31, s46, 0x1c0
	s_lshl_b32 s39, s6, 2
	s_add_u32 s34, s34, s39
	v_or_b32_e32 v5, s31, v1
	s_addc_u32 s35, s35, 0
	v_lshl_add_u64 v[6:7], s[34:35], 0, v[2:3]
	v_lshlrev_b32_e32 v8, 12, v5
	v_mov_b32_e32 v9, v3
	v_lshl_add_u64 v[6:7], v[6:7], 0, v[8:9]
	v_add_co_u32_e32 v8, vcc, s55, v6
	s_lshl_b32 s31, s31, 1
	s_nop 0
	v_addc_co_u32_e32 v9, vcc, 0, v7, vcc
	v_add_co_u32_e32 v10, vcc, s68, v6
	s_add_u32 s34, s93, s31
	s_nop 0
	v_addc_co_u32_e32 v11, vcc, 0, v7, vcc
	v_add_co_u32_e32 v12, vcc, s69, v6
	s_addc_u32 s35, s94, 0
	s_nop 0
	v_addc_co_u32_e32 v13, vcc, 0, v7, vcc
	v_add_co_u32_e32 v14, vcc, s48, v6
	s_nop 1
	v_addc_co_u32_e32 v15, vcc, 0, v7, vcc
	v_add_co_u32_e32 v16, vcc, s70, v6
	s_nop 1
	v_addc_co_u32_e32 v17, vcc, 0, v7, vcc
	v_add_co_u32_e32 v18, vcc, s71, v6
	s_nop 1
	v_addc_co_u32_e32 v19, vcc, 0, v7, vcc
	v_add_co_u32_e32 v20, vcc, s72, v6
	s_nop 1
	v_addc_co_u32_e32 v21, vcc, 0, v7, vcc
	global_load_dword v5, v[6:7], off nt
	global_load_dword v24, v[8:9], off nt
	global_load_dword v25, v[10:11], off nt
	global_load_dword v26, v[12:13], off nt
	global_load_dword v27, v[14:15], off nt
	global_load_dword v28, v[16:17], off nt
	global_load_dword v29, v[18:19], off nt
	global_load_dword v30, v[20:21], off nt
	v_add_co_u32_e32 v8, vcc, s49, v6
	s_nop 1
	v_addc_co_u32_e32 v9, vcc, 0, v7, vcc
	v_add_co_u32_e32 v10, vcc, s73, v6
	s_nop 1
	v_addc_co_u32_e32 v11, vcc, 0, v7, vcc
	v_add_co_u32_e32 v12, vcc, s74, v6
	s_nop 1
	v_addc_co_u32_e32 v13, vcc, 0, v7, vcc
	v_add_co_u32_e32 v14, vcc, s75, v6
	s_nop 1
	v_addc_co_u32_e32 v15, vcc, 0, v7, vcc
	v_add_co_u32_e32 v16, vcc, s2, v6
	s_nop 1
	v_addc_co_u32_e32 v17, vcc, 0, v7, vcc
	v_add_co_u32_e32 v18, vcc, s76, v6
	s_nop 1
	v_addc_co_u32_e32 v19, vcc, 0, v7, vcc
	v_add_co_u32_e32 v20, vcc, s77, v6
	s_nop 1
	v_addc_co_u32_e32 v21, vcc, 0, v7, vcc
	v_add_co_u32_e32 v22, vcc, s78, v6
	s_nop 1
	v_addc_co_u32_e32 v23, vcc, 0, v7, vcc
	global_load_dword v31, v[8:9], off nt
	global_load_dword v32, v[10:11], off nt
	global_load_dword v33, v[12:13], off nt
	global_load_dword v34, v[14:15], off nt
	global_load_dword v35, v[16:17], off nt
	global_load_dword v36, v[18:19], off nt
	global_load_dword v37, v[20:21], off nt
	global_load_dword v38, v[22:23], off nt
	v_add_co_u32_e32 v8, vcc, s3, v6
	s_nop 1
	v_addc_co_u32_e32 v9, vcc, 0, v7, vcc
	v_add_co_u32_e32 v10, vcc, s79, v6
	s_nop 1
	v_addc_co_u32_e32 v11, vcc, 0, v7, vcc
	v_add_co_u32_e32 v12, vcc, s80, v6
	s_nop 1
	v_addc_co_u32_e32 v13, vcc, 0, v7, vcc
	v_add_co_u32_e32 v14, vcc, s81, v6
	s_nop 1
	v_addc_co_u32_e32 v15, vcc, 0, v7, vcc
	v_add_co_u32_e32 v16, vcc, s52, v6
	s_nop 1
	v_addc_co_u32_e32 v17, vcc, 0, v7, vcc
	v_add_co_u32_e32 v18, vcc, s82, v6
	s_nop 1
	v_addc_co_u32_e32 v19, vcc, 0, v7, vcc
	v_add_co_u32_e32 v20, vcc, s83, v6
	s_nop 1
	v_addc_co_u32_e32 v21, vcc, 0, v7, vcc
	v_add_co_u32_e32 v22, vcc, s84, v6
	s_nop 1
	v_addc_co_u32_e32 v23, vcc, 0, v7, vcc
	global_load_dword v39, v[8:9], off nt
	global_load_dword v53, v[10:11], off nt
	global_load_dword v54, v[12:13], off nt
	global_load_dword v55, v[14:15], off nt
	global_load_dword v56, v[16:17], off nt
	global_load_dword v57, v[18:19], off nt
	global_load_dword v58, v[20:21], off nt
	s_nop 0
	global_load_dword v22, v[22:23], off nt
	v_add_co_u32_e32 v8, vcc, s53, v6
	s_nop 1
	v_addc_co_u32_e32 v9, vcc, 0, v7, vcc
	v_add_co_u32_e32 v10, vcc, s85, v6
	s_nop 1
	v_addc_co_u32_e32 v11, vcc, 0, v7, vcc
	v_add_co_u32_e32 v12, vcc, s86, v6
	s_nop 1
	v_addc_co_u32_e32 v13, vcc, 0, v7, vcc
	v_add_co_u32_e32 v14, vcc, s87, v6
	s_nop 1
	v_addc_co_u32_e32 v15, vcc, 0, v7, vcc
	v_add_co_u32_e32 v16, vcc, s54, v6
	s_nop 1
	v_addc_co_u32_e32 v17, vcc, 0, v7, vcc
	v_add_co_u32_e32 v18, vcc, s88, v6
	s_nop 1
	v_addc_co_u32_e32 v19, vcc, 0, v7, vcc
	v_add_co_u32_e32 v20, vcc, s89, v6
	s_nop 1
	v_addc_co_u32_e32 v21, vcc, 0, v7, vcc
	v_add_co_u32_e32 v6, vcc, s90, v6
	s_nop 1
	v_addc_co_u32_e32 v7, vcc, 0, v7, vcc
	global_load_dword v8, v[8:9], off nt
	s_nop 0
	global_load_dword v9, v[10:11], off nt
	s_nop 0
	global_load_dword v10, v[12:13], off nt
	global_load_dword v11, v[14:15], off nt
	s_nop 0
	global_load_dword v12, v[16:17], off nt
	global_load_dword v13, v[18:19], off nt
	global_load_dword v14, v[20:21], off nt
	s_nop 0
	global_load_dword v6, v[6:7], off nt
	s_waitcnt vmcnt(30)
; __device__ __forceinline__ unsigned cvtpk(float lo, float hi) { f32x2_t v = {lo, hi}; f16x2_t b = __builtin_convertvector(v, f16x2_t); return __builtin_bit_cast(unsigned, b); }
; #define LAS __attribute__((address_space(3)))
; __device__ __forceinline__ void p0_transpose_item(const float* W, const float* gain, int K, int N, bf16* WT, LAS float* scr, int item, int lane) {
;     ...
;     for (int i = 0; i < 32; ++i) scr[(2 * i + (lane >> 5)) * 33 + (lane & 31)] = tv[i];
;     asm volatile("s_waitcnt lgkmcnt(0)" ::: "memory");
;     const int c = lane & 7;
; #pragma unroll
;     for (int j = 0; j < 4; ++j) { const int n = (lane >> 3) + 8 * j; const LAS float* s = scr + (8 * c) * 33 + n;
;         u32x4 o; o.x = cvtpk(s[0 * 33], s[1 * 33]); o.y = cvtpk(s[2 * 33], s[3 * 33]); o.z = cvtpk(s[4 * 33], s[5 * 33]); o.w = cvtpk(s[6 * 33], s[7 * 33]);
;         *(u32x4*)(WT + (size_t)(n0 + n) * K + k0 + 8 * c) = o; }
	ds_write2_b32 v40, v5, v24 offset1:66
	s_waitcnt vmcnt(28)
	ds_write2_b32 v40, v25, v26 offset0:132 offset1:198
	s_waitcnt vmcnt(26)
	ds_write2_b32 v46, v27, v28 offset0:8 offset1:74
	s_waitcnt vmcnt(24)
	ds_write2_b32 v46, v29, v30 offset0:140 offset1:206
	s_waitcnt vmcnt(22)
	ds_write2_b32 v47, v31, v32 offset0:16 offset1:82
	s_waitcnt vmcnt(20)
	ds_write2_b32 v47, v33, v34 offset0:148 offset1:214
	s_waitcnt vmcnt(18)
	ds_write2_b32 v48, v35, v36 offset0:24 offset1:90
	s_waitcnt vmcnt(16)
	ds_write2_b32 v48, v37, v38 offset0:156 offset1:222
	s_waitcnt vmcnt(14)
	ds_write2_b32 v49, v39, v53 offset0:32 offset1:98
	s_waitcnt vmcnt(12)
	ds_write2_b32 v49, v54, v55 offset0:164 offset1:230
	s_waitcnt vmcnt(10)
	ds_write2_b32 v50, v56, v57 offset0:40 offset1:106
	s_waitcnt vmcnt(8)
	ds_write2_b32 v50, v58, v22 offset0:172 offset1:238
	s_waitcnt vmcnt(6)
	ds_write2_b32 v51, v8, v9 offset0:48 offset1:114
	s_waitcnt vmcnt(4)
	ds_write2_b32 v51, v10, v11 offset0:180 offset1:246
	s_waitcnt vmcnt(2)
	ds_write2_b32 v52, v12, v13 offset0:56 offset1:122
	s_waitcnt vmcnt(0)
	ds_write2_b32 v52, v14, v6 offset0:188 offset1:254
	s_waitcnt lgkmcnt(0)
	ds_read2_b32 v[10:11], v42 offset0:33 offset1:41
	ds_read2_b32 v[12:13], v42 offset1:8
	ds_read2_b32 v[14:15], v42 offset0:66 offset1:74
	ds_read2_b32 v[16:17], v42 offset0:99 offset1:107
	ds_read2_b32 v[18:19], v42 offset0:132 offset1:140
	ds_read2_b32 v[20:21], v42 offset0:165 offset1:173
	ds_read2_b32 v[22:23], v42 offset0:198 offset1:206
	ds_read2_b32 v[24:25], v42 offset0:231 offset1:239
	v_mov_b32_e32 v5, v3
	v_lshl_add_u64 v[6:7], s[34:35], 0, v[4:5]
	v_or_b32_e32 v5, s6, v41
	v_lshl_add_u64 v[26:27], v[6:7], 0, s[28:29]
	v_lshlrev_b32_e32 v28, 10, v5
	v_mov_b32_e32 v29, v3
	s_waitcnt lgkmcnt(6)
	v_cvt_pk_f16_f32 v6, v12, v10
	s_waitcnt lgkmcnt(4)
	v_cvt_pk_f16_f32 v7, v14, v16
	s_waitcnt lgkmcnt(2)
	v_cvt_pk_f16_f32 v8, v18, v20
	s_waitcnt lgkmcnt(0)
	v_cvt_pk_f16_f32 v9, v22, v24
	v_lshl_add_u64 v[28:29], v[26:27], 0, v[28:29]
	global_store_dwordx4 v[28:29], v[6:9], off sc1
	v_or_b32_e32 v5, s6, v43
	v_lshlrev_b32_e32 v10, 10, v5
	v_cvt_pk_f16_f32 v6, v13, v11
	v_cvt_pk_f16_f32 v7, v15, v17
	v_cvt_pk_f16_f32 v8, v19, v21
	v_cvt_pk_f16_f32 v9, v23, v25
	ds_read2_b32 v[12:13], v42 offset0:49 offset1:57
	ds_read2_b32 v[14:15], v42 offset0:16 offset1:24
	ds_read2_b32 v[16:17], v42 offset0:82 offset1:90
	ds_read2_b32 v[18:19], v42 offset0:115 offset1:123
	ds_read2_b32 v[20:21], v42 offset0:148 offset1:156
	ds_read2_b32 v[22:23], v42 offset0:181 offset1:189
	ds_read2_b32 v[24:25], v42 offset0:214 offset1:222
	ds_read2_b32 v[28:29], v42 offset0:247 offset1:255
	v_mov_b32_e32 v11, v3
	v_lshl_add_u64 v[10:11], v[26:27], 0, v[10:11]
	v_or_b32_e32 v5, s6, v44
	global_store_dwordx4 v[10:11], v[6:9], off sc1
	v_lshlrev_b32_e32 v10, 10, v5
	v_mov_b32_e32 v11, v3
	s_waitcnt lgkmcnt(6)
	v_cvt_pk_f16_f32 v6, v14, v12
	s_waitcnt lgkmcnt(4)
	v_cvt_pk_f16_f32 v7, v16, v18
	s_waitcnt lgkmcnt(2)
	v_cvt_pk_f16_f32 v8, v20, v22
	s_waitcnt lgkmcnt(0)
	v_cvt_pk_f16_f32 v9, v24, v28
	v_lshl_add_u64 v[10:11], v[26:27], 0, v[10:11]
	v_or_b32_e32 v5, s6, v45
	global_store_dwordx4 v[10:11], v[6:9], off sc1
	v_lshlrev_b32_e32 v10, 10, v5
	v_mov_b32_e32 v11, v3
	v_cvt_pk_f16_f32 v6, v15, v13
	v_cvt_pk_f16_f32 v7, v17, v19
	v_cvt_pk_f16_f32 v8, v21, v23
	v_cvt_pk_f16_f32 v9, v25, v29
	v_lshl_add_u64 v[10:11], v[26:27], 0, v[10:11]
	global_store_dwordx4 v[10:11], v[6:9], off sc1
	s_waitcnt lgkmcnt(0)

; __device__ __forceinline__ void p0_transpose_item(const float* W, const float* gain, int K, int N, bf16* WT, LAS float* scr, int item, int lane) {
;     const int nblk = N / 32, kb = item / nblk, nb = item % nblk, k0 = 64 * kb, n0 = 32 * nb;
;     float tv[32];
; #pragma unroll
;     for (int i = 0; i < 32; ++i) { const int kk = 2 * i + (lane >> 5); tv[i] = W[(size_t)(k0 + kk) * N + n0 + (lane & 31)]; }
;     if (gain) {
.LBB0_30:
	s_andn2_b64 vcc, exec, s[34:35]
	s_cbranch_vccnz .LBB0_9
	s_mul_i32 s31, s30, 0x2600000
	s_mul_hi_i32 s6, s30, 0x2600000
	s_add_u32 s31, s12, s31
	s_mul_hi_i32 s34, s38, 0x6bca1af3
	s_addc_u32 s6, s13, s6
	s_lshr_b32 s35, s34, 31
	s_ashr_i32 s34, s34, 7
	s_add_i32 s34, s34, s35
	s_mul_i32 s35, s34, 0x130
	s_sub_i32 s35, s38, s35
	s_lshl_b32 s38, s34, 6
	s_lshl_b32 s34, s35, 5
	s_ashr_i32 s35, s34, 31
	s_lshl_b64 s[96:97], s[34:35], 2
	s_add_u32 s96, s31, s96
	v_or_b32_e32 v38, s38, v1
	s_addc_u32 s97, s6, s97
	v_lshl_add_u64 v[30:31], s[96:97], 0, v[2:3]
	v_or_b32_e32 v5, 2, v38
	v_mad_i64_i32 v[8:9], s[96:97], v5, s91, v[30:31]
	v_or_b32_e32 v5, 4, v38
	v_mad_i64_i32 v[10:11], s[96:97], v5, s91, v[30:31]
	v_or_b32_e32 v5, 6, v38
	v_mad_i64_i32 v[12:13], s[96:97], v5, s91, v[30:31]
	v_or_b32_e32 v5, 8, v38
	v_mad_i64_i32 v[14:15], s[96:97], v5, s91, v[30:31]
	v_or_b32_e32 v5, 10, v38
	v_mad_i64_i32 v[16:17], s[96:97], v5, s91, v[30:31]
	v_or_b32_e32 v5, 12, v38
	v_mad_i64_i32 v[18:19], s[96:97], v5, s91, v[30:31]
	v_or_b32_e32 v5, 14, v38
	v_mad_i64_i32 v[6:7], s[96:97], v38, s91, v[30:31]
	v_mad_i64_i32 v[20:21], s[96:97], v5, s91, v[30:31]
	v_or_b32_e32 v5, 16, v38
	global_load_dword v6, v[6:7], off nt
	s_nop 0
	global_load_dword v7, v[8:9], off nt
	s_nop 0
	global_load_dword v8, v[10:11], off nt
	global_load_dword v9, v[12:13], off nt
	s_nop 0
	global_load_dword v10, v[14:15], off nt
	global_load_dword v11, v[16:17], off nt
	global_load_dword v12, v[18:19], off nt
	global_load_dword v13, v[20:21], off nt
	v_mad_i64_i32 v[14:15], s[96:97], v5, s91, v[30:31]
	v_or_b32_e32 v5, 18, v38
	v_mad_i64_i32 v[16:17], s[96:97], v5, s91, v[30:31]
	v_or_b32_e32 v5, 20, v38
	v_mad_i64_i32 v[18:19], s[96:97], v5, s91, v[30:31]
	v_or_b32_e32 v5, 22, v38
	v_mad_i64_i32 v[20:21], s[96:97], v5, s91, v[30:31]
	v_or_b32_e32 v5, 24, v38
	v_mad_i64_i32 v[22:23], s[96:97], v5, s91, v[30:31]
	v_or_b32_e32 v5, 26, v38
	v_mad_i64_i32 v[24:25], s[96:97], v5, s91, v[30:31]
	v_or_b32_e32 v5, 28, v38
	v_mad_i64_i32 v[26:27], s[96:97], v5, s91, v[30:31]
	v_or_b32_e32 v5, 30, v38
	v_mad_i64_i32 v[28:29], s[96:97], v5, s91, v[30:31]
	v_or_b32_e32 v5, 32, v38
	global_load_dword v14, v[14:15], off nt
	s_nop 0
	global_load_dword v15, v[16:17], off nt
	s_nop 0
	global_load_dword v16, v[18:19], off nt
	global_load_dword v17, v[20:21], off nt
	s_nop 0
	global_load_dword v18, v[22:23], off nt
	global_load_dword v19, v[24:25], off nt
	global_load_dword v20, v[26:27], off nt
	global_load_dword v21, v[28:29], off nt
	v_mad_i64_i32 v[22:23], s[96:97], v5, s91, v[30:31]
	v_or_b32_e32 v5, 34, v38
	v_mad_i64_i32 v[24:25], s[96:97], v5, s91, v[30:31]
	v_or_b32_e32 v5, 36, v38
	v_mad_i64_i32 v[26:27], s[96:97], v5, s91, v[30:31]
	v_or_b32_e32 v5, 38, v38
	v_mad_i64_i32 v[28:29], s[96:97], v5, s91, v[30:31]
	v_or_b32_e32 v5, 40, v38
	v_mad_i64_i32 v[32:33], s[96:97], v5, s91, v[30:31]
	v_or_b32_e32 v5, 42, v38
	v_mad_i64_i32 v[34:35], s[96:97], v5, s91, v[30:31]
	v_or_b32_e32 v5, 44, v38
	v_mad_i64_i32 v[36:37], s[96:97], v5, s91, v[30:31]
	v_or_b32_e32 v5, 46, v38
	v_mad_i64_i32 v[54:55], s[96:97], v5, s91, v[30:31]
	v_or_b32_e32 v5, 48, v38
	global_load_dword v22, v[22:23], off nt
	s_nop 0
	global_load_dword v23, v[24:25], off nt
	s_nop 0
	global_load_dword v24, v[26:27], off nt
	global_load_dword v25, v[28:29], off nt
	s_nop 0
	global_load_dword v26, v[32:33], off nt
	global_load_dword v27, v[34:35], off nt
	global_load_dword v28, v[36:37], off nt
	global_load_dword v29, v[54:55], off nt
	v_mad_i64_i32 v[32:33], s[96:97], v5, s91, v[30:31]
	v_or_b32_e32 v5, 50, v38
	v_mad_i64_i32 v[34:35], s[96:97], v5, s91, v[30:31]
	v_or_b32_e32 v5, 52, v38
	v_mad_i64_i32 v[36:37], s[96:97], v5, s91, v[30:31]
	v_or_b32_e32 v5, 54, v38
	v_mad_i64_i32 v[54:55], s[96:97], v5, s91, v[30:31]
	v_or_b32_e32 v5, 56, v38
	v_mad_i64_i32 v[56:57], s[96:97], v5, s91, v[30:31]
	v_or_b32_e32 v5, 58, v38
	v_mad_i64_i32 v[58:59], s[96:97], v5, s91, v[30:31]
	v_or_b32_e32 v5, 60, v38
	v_mad_i64_i32 v[60:61], s[96:97], v5, s91, v[30:31]
	v_or_b32_e32 v5, 62, v38
	v_mad_i64_i32 v[62:63], s[96:97], v5, s91, v[30:31]
	global_load_dword v30, v[32:33], off nt
	global_load_dword v31, v[34:35], off nt
	s_nop 0
	global_load_dword v32, v[36:37], off nt
	global_load_dword v33, v[54:55], off nt
	s_nop 0
	global_load_dword v36, v[56:57], off nt
	global_load_dword v37, v[58:59], off nt
	global_load_dword v34, v[60:61], off nt
	global_load_dword v35, v[62:63], off nt
	s_andn2_b64 vcc, exec, s[4:5]
	s_cbranch_vccnz .LBB0_8
; __device__ __forceinline__ void p0_transpose_item(const float* W, const float* gain, int K, int N, bf16* WT, LAS float* scr, int item, int lane) {
;     ...
;     if (gain) {
; #pragma unroll
;         for (int i = 0; i < 32; ++i) tv[i] *= gain[k0 + 2 * i + (lane >> 5)]; }
	s_lshl_b32 s30, s30, 10
	s_ashr_i32 s31, s30, 31
	s_lshl_b64 s[30:31], s[30:31], 2
	s_add_u32 s30, s10, s30
	v_ashrrev_i32_e32 v39, 31, v38
	s_addc_u32 s31, s11, s31
	v_lshl_add_u64 v[38:39], v[38:39], 2, s[30:31]
	global_load_dword v54, v[38:39], off nt
	global_load_dword v55, v[38:39], off offset:8 nt
	global_load_dword v56, v[38:39], off offset:16 nt
	global_load_dword v57, v[38:39], off offset:24 nt
	global_load_dword v58, v[38:39], off offset:32 nt
	global_load_dword v59, v[38:39], off offset:40 nt
	global_load_dword v60, v[38:39], off offset:48 nt
	global_load_dword v61, v[38:39], off offset:56 nt
	global_load_dword v62, v[38:39], off offset:64 nt
	global_load_dword v63, v[38:39], off offset:72 nt
	global_load_dword v64, v[38:39], off offset:80 nt
	global_load_dword v65, v[38:39], off offset:88 nt
	global_load_dword v66, v[38:39], off offset:96 nt
	global_load_dword v67, v[38:39], off offset:104 nt
	global_load_dword v68, v[38:39], off offset:112 nt
	global_load_dword v69, v[38:39], off offset:120 nt
	global_load_dword v70, v[38:39], off offset:128 nt
	global_load_dword v71, v[38:39], off offset:136 nt
	global_load_dword v72, v[38:39], off offset:144 nt
	global_load_dword v73, v[38:39], off offset:152 nt
	global_load_dword v74, v[38:39], off offset:160 nt
	global_load_dword v75, v[38:39], off offset:168 nt
	global_load_dword v76, v[38:39], off offset:176 nt
	global_load_dword v77, v[38:39], off offset:184 nt
	global_load_dword v78, v[38:39], off offset:192 nt
	global_load_dword v79, v[38:39], off offset:200 nt
	global_load_dword v80, v[38:39], off offset:208 nt
	global_load_dword v81, v[38:39], off offset:216 nt
	global_load_dword v82, v[38:39], off offset:224 nt
	global_load_dword v83, v[38:39], off offset:232 nt
	global_load_dword v84, v[38:39], off offset:240 nt
	global_load_dword v85, v[38:39], off offset:248 nt
	s_waitcnt vmcnt(30)
	v_pk_mul_f32 v[6:7], v[6:7], v[54:55]
	s_waitcnt vmcnt(28)
	v_pk_mul_f32 v[8:9], v[8:9], v[56:57]
	s_waitcnt vmcnt(26)
	v_pk_mul_f32 v[10:11], v[10:11], v[58:59]
	s_waitcnt vmcnt(24)
	v_pk_mul_f32 v[12:13], v[12:13], v[60:61]
	s_waitcnt vmcnt(22)
	v_pk_mul_f32 v[14:15], v[14:15], v[62:63]
	s_waitcnt vmcnt(20)
	v_pk_mul_f32 v[16:17], v[16:17], v[64:65]
	s_waitcnt vmcnt(18)
	v_pk_mul_f32 v[18:19], v[18:19], v[66:67]
	s_waitcnt vmcnt(16)
	v_pk_mul_f32 v[20:21], v[20:21], v[68:69]
	s_waitcnt vmcnt(14)
	v_pk_mul_f32 v[22:23], v[22:23], v[70:71]
	s_waitcnt vmcnt(12)
	v_pk_mul_f32 v[24:25], v[24:25], v[72:73]
	s_waitcnt vmcnt(10)
	v_pk_mul_f32 v[26:27], v[26:27], v[74:75]
	s_waitcnt vmcnt(8)
	v_pk_mul_f32 v[28:29], v[28:29], v[76:77]
	s_waitcnt vmcnt(6)
	v_pk_mul_f32 v[30:31], v[30:31], v[78:79]
	s_waitcnt vmcnt(4)
	v_pk_mul_f32 v[32:33], v[32:33], v[80:81]
	s_waitcnt vmcnt(2)
	v_pk_mul_f32 v[36:37], v[36:37], v[82:83]
	s_waitcnt vmcnt(0)
	v_pk_mul_f32 v[34:35], v[34:35], v[84:85]
	s_branch .LBB0_8

; __device__ __forceinline__ void attn_load(int tid, int u, const bf16* P, const float* ropeA, u32x4 (&st)[10], f32x4 (&rc)[4]) {
;     const AttnU a = attn_decode(u); const int rstart = a.r << (12 - a.dsh);
; #pragma unroll
;     for (int it = 0; it < 10; ++it) { const int idx = it * 512 + tid, row = idx >> 3, ch = idx & 7;
;         const int sect = it < 2 ? 0 : (it < 6 ? 1 : 2); const int li = row - (sect == 0 ? 0 : (sect == 1 ? 128 : 384));
;         const int sub = (sect == 0 ? a.n * 128 : (a.n - 1) * 128) + li;
;         u32x4 v = (u32x4){0u, 0u, 0u, 0u};
;         if (sub >= 0) v = *(const u32x4*)(P + PL_A + ((size_t)((a.bl * 3 + sect) * 24 + a.g * 8 + a.h) * 4096 + rstart + sub) * 64 + ch * 8);
;         st[it] = v; }
.LBB0_477:
	s_or_b64 exec, exec, s[18:19]
	s_cmpk_gt_i32 s5, 0xcef
	s_cselect_b64 s[18:19], -1, 0
	s_and_b64 vcc, exec, s[18:19]
	s_cbranch_vccnz .LBB0_501
	s_add_i32 s14, s5, 0xffffff10
	s_mul_hi_i32 s15, s14, 0x2aaaaaab
	s_lshr_b32 s20, s15, 31
	s_ashr_i32 s15, s15, 7
	s_add_i32 s26, s15, s20
	s_mul_i32 s15, s26, 0xfffffd00
	s_add_i32 s15, s15, s14
	s_ashr_i32 s21, s15, 8
	s_and_b32 s20, s14, 31
	s_bfe_u32 s22, s14, 0x30005
	s_lshl_b32 s14, s21, 1
	s_sub_i32 s23, 5, s14
	s_lshr_b32 s15, s20, s23
	s_lshl_b32 s23, -1, s23
	s_andn2_b32 s23, s20, s23
	s_sub_i32 s20, 12, s14
	s_lshl_b32 s24, s23, 7
	v_mov_b32_e32 v6, v1
	v_mov_b32_e32 v7, v1
	s_lshl_b32 s20, s15, s20
	s_lshl_b32 s21, s21, 3
	v_lshl_add_u64 v[44:45], s[74:75], 0, v[0:1]
	v_add_u32_e32 v0, s24, v68
	v_mov_b32_e32 v4, v1
	v_mov_b32_e32 v5, v1
	v_mov_b64_e32 v[10:11], v[6:7]
	s_or_b32 s25, s21, s22
	s_ashr_i32 s21, s20, 31
	v_cmp_lt_i32_e32 vcc, -1, v0
	s_mulk_i32 s26, 0x48
	v_mov_b64_e32 v[8:9], v[4:5]
	s_and_saveexec_b64 s[22:23], vcc
	s_cbranch_execz .LBB0_480
	s_add_i32 s28, s25, s26
	s_ashr_i32 s29, s28, 31
	v_lshl_add_u64 v[8:9], v[0:1], 0, s[20:21]
	s_lshl_b64 s[28:29], s[28:29], 19
	v_lshlrev_b64 v[8:9], 7, v[8:9]
	v_lshl_add_u64 v[10:11], v[44:45], 0, s[28:29]
	v_lshl_add_u64 v[8:9], v[10:11], 0, v[8:9]
	global_load_dwordx4 v[8:11], v[8:9], off nt
.LBB0_480:
	s_or_b64 exec, exec, s[22:23]
	v_add_u32_e32 v0, s24, v3
	v_cmp_lt_i32_e32 vcc, -1, v0
	s_and_saveexec_b64 s[22:23], vcc
	s_cbranch_execz .LBB0_482
	s_add_i32 s28, s25, s26
	s_ashr_i32 s29, s28, 31
	v_lshl_add_u64 v[4:5], v[0:1], 0, s[20:21]
	s_lshl_b64 s[28:29], s[28:29], 19
	v_lshlrev_b64 v[4:5], 7, v[4:5]
	v_lshl_add_u64 v[6:7], v[44:45], 0, s[28:29]
	v_lshl_add_u64 v[4:5], v[6:7], 0, v[4:5]
	global_load_dwordx4 v[4:7], v[4:5], off nt
.LBB0_482:
	s_or_b64 exec, exec, s[22:23]
	s_add_i32 s27, s24, 0xffffff80
	v_add_u32_e32 v16, s27, v2
	v_mov_b32_e32 v2, v1
	v_mov_b32_e32 v3, v1
	s_movk_i32 s22, 0x7f
	v_mov_b32_e32 v0, v1
	v_mov_b64_e32 v[14:15], v[2:3]
	v_cmp_lt_i32_e32 vcc, s22, v16
	v_mov_b64_e32 v[12:13], v[0:1]
	s_and_saveexec_b64 s[22:23], vcc
	s_cbranch_execz .LBB0_484
	s_add_i32 s28, s26, s25
	s_add_i32 s28, s28, 24
	v_add_u32_e32 v12, 0xffffff80, v16
	s_ashr_i32 s29, s28, 31
	v_mov_b32_e32 v13, v1
	v_lshl_add_u64 v[12:13], v[12:13], 0, s[20:21]
	s_lshl_b64 s[28:29], s[28:29], 19
	v_lshlrev_b64 v[12:13], 7, v[12:13]
	v_lshl_add_u64 v[14:15], v[44:45], 0, s[28:29]
	v_lshl_add_u64 v[12:13], v[14:15], 0, v[12:13]
	global_load_dwordx4 v[12:15], v[12:13], off nt
.LBB0_484:
	s_or_b64 exec, exec, s[22:23]
	v_add_u32_e32 v20, s27, v67
	s_movk_i32 s22, 0x7f
	v_mov_b64_e32 v[18:19], v[2:3]
	v_cmp_lt_i32_e32 vcc, s22, v20
	v_mov_b64_e32 v[16:17], v[0:1]
	s_and_saveexec_b64 s[22:23], vcc
	s_cbranch_execz .LBB0_486
	s_add_i32 s28, s26, s25
	s_add_i32 s28, s28, 24
	v_add_u32_e32 v0, 0xffffff80, v20
	s_ashr_i32 s29, s28, 31
	v_lshl_add_u64 v[2:3], v[0:1], 0, s[20:21]
	s_lshl_b64 s[28:29], s[28:29], 19
	v_lshlrev_b64 v[2:3], 7, v[2:3]
	v_lshl_add_u64 v[16:17], v[44:45], 0, s[28:29]
	v_lshl_add_u64 v[2:3], v[16:17], 0, v[2:3]
	global_load_dwordx4 v[16:19], v[2:3], off nt
.LBB0_486:
	s_or_b64 exec, exec, s[22:23]
	v_mov_b32_e32 v2, v1
	v_mov_b32_e32 v3, v1
	v_add_u32_e32 v24, s27, v66
	s_movk_i32 s22, 0x7f
	v_mov_b32_e32 v0, v1
	v_mov_b64_e32 v[22:23], v[2:3]
	v_cmp_lt_i32_e32 vcc, s22, v24
	v_mov_b64_e32 v[20:21], v[0:1]
	s_and_saveexec_b64 s[22:23], vcc
	s_cbranch_execz .LBB0_488
	s_add_i32 s28, s26, s25
	s_add_i32 s28, s28, 24
	v_add_u32_e32 v20, 0xffffff80, v24
	s_ashr_i32 s29, s28, 31
	v_mov_b32_e32 v21, v1
	v_lshl_add_u64 v[20:21], v[20:21], 0, s[20:21]
	s_lshl_b64 s[28:29], s[28:29], 19
	v_lshlrev_b64 v[20:21], 7, v[20:21]
	v_lshl_add_u64 v[22:23], v[44:45], 0, s[28:29]
	v_lshl_add_u64 v[20:21], v[22:23], 0, v[20:21]
	global_load_dwordx4 v[20:23], v[20:21], off nt
.LBB0_488:
	s_or_b64 exec, exec, s[22:23]
	v_add_u32_e32 v28, s27, v65
	s_movk_i32 s22, 0x7f
	v_mov_b64_e32 v[26:27], v[2:3]
	v_cmp_lt_i32_e32 vcc, s22, v28
	v_mov_b64_e32 v[24:25], v[0:1]
	s_and_saveexec_b64 s[22:23], vcc
	s_cbranch_execz .LBB0_490
	s_add_i32 s28, s26, s25
	s_add_i32 s28, s28, 24
	v_add_u32_e32 v0, 0xffffff80, v28
	s_ashr_i32 s29, s28, 31
	v_lshl_add_u64 v[2:3], v[0:1], 0, s[20:21]
	s_lshl_b64 s[28:29], s[28:29], 19
	v_lshlrev_b64 v[2:3], 7, v[2:3]
	v_lshl_add_u64 v[24:25], v[44:45], 0, s[28:29]
	v_lshl_add_u64 v[2:3], v[24:25], 0, v[2:3]
	global_load_dwordx4 v[24:27], v[2:3], off nt
; __device__ __forceinline__ void attn_load(int tid, int u, const bf16* P, const float* ropeA, u32x4 (&st)[10], f32x4 (&rc)[4]) {
;     ...
;     for (int it = 0; it < 10; ++it) { const int idx = it * 512 + tid, row = idx >> 3, ch = idx & 7;
;         const int sect = it < 2 ? 0 : (it < 6 ? 1 : 2); const int li = row - (sect == 0 ? 0 : (sect == 1 ? 128 : 384));
;         const int sub = (sect == 0 ? a.n * 128 : (a.n - 1) * 128) + li;
;         u32x4 v = (u32x4){0u, 0u, 0u, 0u};
;         if (sub >= 0) v = *(const u32x4*)(P + PL_A + ((size_t)((a.bl * 3 + sect) * 24 + a.g * 8 + a.h) * 4096 + rstart + sub) * 64 + ch * 8);
;         st[it] = v; }
;     rc[0] = rc[1] = rc[2] = rc[3] = (f32x4){0.f, 0.f, 0.f, 0.f};
;     if (tid < 384) { const int sub = (tid < 128) ? (a.n * 128 + tid) : ((a.n - 1) * 128 + tid - 128); const int t = sub >= 0 ? ((sub << a.dsh) + a.r) : 0;
;         rc[0] = *(const f32x4*)(ropeA + t * 8); rc[1] = *(const f32x4*)(ropeA + t * 8 + 4); rc[2] = *(const f32x4*)(ropeA + SEQ * 8 + t * 8); rc[3] = *(const f32x4*)(ropeA + SEQ * 8 + t * 8 + 4); }
.LBB0_490:
	s_or_b64 exec, exec, s[22:23]
	v_mov_b32_e32 v2, v1
	v_mov_b32_e32 v3, v1
	v_add_u32_e32 v32, s27, v63
	s_movk_i32 s22, 0x17f
	v_mov_b32_e32 v0, v1
	v_mov_b64_e32 v[30:31], v[2:3]
	v_cmp_lt_i32_e32 vcc, s22, v32
	v_mov_b64_e32 v[28:29], v[0:1]
	s_and_saveexec_b64 s[22:23], vcc
	s_cbranch_execz .LBB0_492
	s_add_i32 s28, s26, s25
	s_add_i32 s28, s28, 48
	v_add_u32_e32 v28, 0xfffffe80, v32
	s_ashr_i32 s29, s28, 31
	v_mov_b32_e32 v29, v1
	v_lshl_add_u64 v[28:29], v[28:29], 0, s[20:21]
	s_lshl_b64 s[28:29], s[28:29], 19
	v_lshlrev_b64 v[28:29], 7, v[28:29]
	v_lshl_add_u64 v[30:31], v[44:45], 0, s[28:29]
	v_lshl_add_u64 v[28:29], v[30:31], 0, v[28:29]
	global_load_dwordx4 v[28:31], v[28:29], off nt
.LBB0_492:
	s_or_b64 exec, exec, s[22:23]
	v_add_u32_e32 v36, s27, v62
	s_movk_i32 s22, 0x17f
	v_mov_b64_e32 v[34:35], v[2:3]
	v_cmp_lt_i32_e32 vcc, s22, v36
	v_mov_b64_e32 v[32:33], v[0:1]
	s_and_saveexec_b64 s[22:23], vcc
	s_cbranch_execz .LBB0_494
	s_add_i32 s28, s26, s25
	s_add_i32 s28, s28, 48
	v_add_u32_e32 v0, 0xfffffe80, v36
	s_ashr_i32 s29, s28, 31
	v_lshl_add_u64 v[2:3], v[0:1], 0, s[20:21]
	s_lshl_b64 s[28:29], s[28:29], 19
	v_lshlrev_b64 v[2:3], 7, v[2:3]
	v_lshl_add_u64 v[32:33], v[44:45], 0, s[28:29]
	v_lshl_add_u64 v[2:3], v[32:33], 0, v[2:3]
	global_load_dwordx4 v[32:35], v[2:3], off nt
.LBB0_494:
	s_or_b64 exec, exec, s[22:23]
	v_mov_b32_e32 v2, v1
	v_mov_b32_e32 v3, v1
	v_add_u32_e32 v40, s27, v61
	s_movk_i32 s22, 0x17f
	v_mov_b32_e32 v0, v1
	v_mov_b64_e32 v[38:39], v[2:3]
	v_cmp_lt_i32_e32 vcc, s22, v40
	v_mov_b64_e32 v[36:37], v[0:1]
	s_and_saveexec_b64 s[22:23], vcc
	s_cbranch_execz .LBB0_496
	s_add_i32 s28, s26, s25
	s_add_i32 s28, s28, 48
	v_add_u32_e32 v36, 0xfffffe80, v40
	s_ashr_i32 s29, s28, 31
	v_mov_b32_e32 v37, v1
	v_lshl_add_u64 v[36:37], v[36:37], 0, s[20:21]
	s_lshl_b64 s[28:29], s[28:29], 19
	v_lshlrev_b64 v[36:37], 7, v[36:37]
	v_lshl_add_u64 v[38:39], v[44:45], 0, s[28:29]
	v_lshl_add_u64 v[36:37], v[38:39], 0, v[36:37]
	global_load_dwordx4 v[36:39], v[36:37], off nt
.LBB0_496:
	s_or_b64 exec, exec, s[22:23]
	v_add_u32_e32 v46, s27, v60
	s_movk_i32 s22, 0x17f
	v_mov_b64_e32 v[42:43], v[2:3]
	v_cmp_lt_i32_e32 vcc, s22, v46
	v_mov_b64_e32 v[40:41], v[0:1]
	s_and_saveexec_b64 s[22:23], vcc
	s_cbranch_execz .LBB0_498
	s_add_i32 s25, s26, s25
	s_add_i32 s26, s25, 48
	v_add_u32_e32 v0, 0xfffffe80, v46
	s_ashr_i32 s27, s26, 31
	v_lshl_add_u64 v[2:3], v[0:1], 0, s[20:21]
	s_lshl_b64 s[20:21], s[26:27], 19
	v_lshlrev_b64 v[2:3], 7, v[2:3]
	v_lshl_add_u64 v[40:41], v[44:45], 0, s[20:21]
	v_lshl_add_u64 v[2:3], v[40:41], 0, v[2:3]
	global_load_dwordx4 v[40:43], v[2:3], off nt
.LBB0_498:
	s_or_b64 exec, exec, s[22:23]
	v_mov_b32_e32 v47, 0
	v_mov_b32_e32 v46, 0
	v_mov_b32_e32 v45, 0
	v_mov_b32_e32 v44, 0
	v_mov_b32_e32 v59, 0
	v_mov_b32_e32 v58, 0
	v_mov_b32_e32 v57, 0
	v_mov_b32_e32 v56, 0
	v_mov_b32_e32 v51, 0
	v_mov_b32_e32 v50, 0
	v_mov_b32_e32 v49, 0
	v_mov_b32_e32 v48, 0
	v_mov_b32_e32 v55, 0
	v_mov_b32_e32 v54, 0
	v_mov_b32_e32 v53, 0
	v_mov_b32_e32 v52, 0
	s_and_saveexec_b64 s[20:21], s[38:39]
	s_cbranch_execz .LBB0_500
	s_movk_i32 s22, 0x80
	v_add_u32_e32 v0, 0xffffff00, v64
	v_cmp_gt_i32_e32 vcc, s22, v64
	s_nop 1
	v_cndmask_b32_e32 v0, v0, v64, vcc
	v_add_u32_e32 v0, s24, v0
	v_lshlrev_b32_e32 v2, s14, v0
	v_add_lshl_u32 v2, v2, s15, 3
	v_cmp_lt_i32_e32 vcc, -1, v0
	v_readlane_b32 s14, v253, 19
	v_readlane_b32 s15, v253, 20
	v_cndmask_b32_e32 v2, 0, v2, vcc
	v_ashrrev_i32_e32 v3, 31, v2
	v_lshlrev_b64 v[2:3], 2, v[2:3]
	v_lshl_add_u64 v[44:45], s[14:15], 0, v[2:3]
	v_readlane_b32 s14, v254, 38
	v_readlane_b32 s15, v254, 39
	global_load_dwordx4 v[52:55], v[44:45], off nt
	global_load_dwordx4 v[48:51], v[44:45], off offset:16 nt
	v_lshl_add_u64 v[2:3], s[14:15], 0, v[2:3]
	global_load_dwordx4 v[56:59], v[2:3], off nt
	global_load_dwordx4 v[44:47], v[2:3], off offset:16 nt
